# c1 sol-init loads batched; scan step no longer waits on next-chunk prefetch; hyena zin-load + final loops batched; hyconv loads in one round trip
# speedup vs baseline: 1.0568x; 1.0568x over previous
; DI void phase_hyconv(const Ctx& c) {
;     ...
;     {
;       const int tr = tid >> 3, cs = (tid & 7) * 8;
;       const int tok = t0 + tr, n = tok & (L - 1);
;       float cur[8], prv[8], nxt[8];
;       unpack8(*(const uint4*)(P + (size_t)tok * 1536 + c0 + cs), cur);
;       if (n > 0) unpack8(*(const uint4*)(P + (size_t)(tok - 1) * 1536 + c0 + cs), prv);
;       else { for (int e = 0; e < 8; ++e) prv[e] = 0.f; }
;       if (n < L - 1) unpack8(*(const uint4*)(P + (size_t)(tok + 1) * 1536 + c0 + cs), nxt);
;       else { for (int e = 0; e < 8; ++e) nxt[e] = 0.f; }
; #pragma unroll
;       for (int e = 0; e < 8; ++e) {
;         const int ch = c0 + cs + e;
;         const float v = prv[e] * cw[ch] + cur[e] * cw[1536 + ch] + nxt[e] * cw[3072 + ch] + cb[ch];
;         tileT[(cs + e) * 72 + tr] = f2bf(v);
;       }
;     }
;     __syncthreads();
;     {
;       const int ch = tid >> 3, ts = (tid & 7) * 8;
;       const int cg_ = c0 + ch, part = cg_ >> 9, cc = cg_ & 511;
;       const int seq = t0 >> c.logL, n0 = t0 & (L - 1);
;       bf16* dst = (bf16*)(c.ws + OFF_X1 + (size_t)part * SZ_T512) + ((size_t)(seq * 512 + cc)) * L + n0 + ts;
;       *(uint4*)dst = *(const uint4*)(tileT + ch * 72 + ts);
;     }
;     __syncthreads();
.LBB0_269:
	s_or_b64 exec, exec, s[8:9]
	v_or_b32_e32 v26, s6, v6
	v_ashrrev_i32_e32 v27, 31, v26
	v_lshlrev_b64 v[50:51], 2, v[26:27]
	v_lshl_add_u64 v[46:47], s[0:1], 0, v[50:51]
	s_mov_b64 s[8:9], 0x1800
	s_movk_i32 s7, 0x1000
	v_lshl_add_u64 v[26:27], v[46:47], 0, s[8:9]
	v_add_co_u32_e32 v30, vcc, s7, v46
	global_load_dwordx4 v[26:29], v[26:27], off offset:16
	s_nop 0
	v_addc_co_u32_e32 v31, vcc, 0, v47, vcc
	s_mov_b64 s[8:9], 0x3000
	s_movk_i32 s7, 0x3000
	global_load_dwordx4 v[30:33], v[30:31], off offset:2048
	s_nop 0
	global_load_dwordx4 v[34:37], v[46:47], off offset:16
	global_load_dwordx4 v[38:41], v[46:47], off
	v_lshl_add_u64 v[42:43], v[46:47], 0, s[8:9]
	v_add_co_u32_e32 v46, vcc, s7, v46
	global_load_dwordx4 v[42:45], v[42:43], off offset:16
	s_nop 0
	v_addc_co_u32_e32 v47, vcc, 0, v47, vcc
	global_load_dwordx4 v[46:49], v[46:47], off
	v_lshl_add_u64 v[54:55], s[4:5], 0, v[50:51]
	global_load_dwordx4 v[50:53], v[54:55], off offset:16
	s_nop 0
	global_load_dwordx4 v[54:57], v[54:55], off
	s_add_i32 s7, s12, s14
	s_waitcnt vmcnt(8)
	v_lshlrev_b32_e32 v11, 16, v230
	v_and_b32_e32 v12, 0xffff0000, v230
	v_lshlrev_b32_e32 v13, 16, v231
	v_and_b32_e32 v14, 0xffff0000, v231
	v_lshlrev_b32_e32 v15, 16, v232
	v_and_b32_e32 v16, 0xffff0000, v232
	v_lshlrev_b32_e32 v17, 16, v233
	v_and_b32_e32 v18, 0xffff0000, v233
	v_lshlrev_b32_e32 v10, 16, v234
	v_and_b32_e32 v19, 0xffff0000, v234
	v_lshlrev_b32_e32 v20, 16, v235
	v_and_b32_e32 v21, 0xffff0000, v235
	v_lshlrev_b32_e32 v22, 16, v236
	v_and_b32_e32 v23, 0xffff0000, v236
	v_lshlrev_b32_e32 v24, 16, v237
	v_and_b32_e32 v25, 0xffff0000, v237
	v_lshlrev_b32_e32 v63, 16, v3
	v_and_b32_e32 v64, 0xffff0000, v3
	v_add_u32_e32 v3, s6, v7
	v_lshlrev_b32_e32 v59, 16, v2
	v_and_b32_e32 v62, 0xffff0000, v2
	v_ashrrev_i32_e32 v2, 9, v3
	v_and_b32_e32 v58, 0x1ff, v3
	s_ashr_i32 s6, s7, s87
	s_and_b32 s82, s7, s18
	v_ashrrev_i32_e32 v3, 31, v2
	v_lshl_or_b32 v58, s6, 9, v58
	v_readlane_b32 s6, v228, 10
	v_lshlrev_b32_e32 v65, 16, v4
	v_and_b32_e32 v4, 0xffff0000, v4
	v_lshlrev_b32_e32 v66, 16, v5
	v_and_b32_e32 v5, 0xffff0000, v5
	v_lshlrev_b64 v[2:3], 25, v[2:3]
	v_readlane_b32 s7, v228, 11
	s_add_i32 s13, s13, s38
	s_add_i32 s12, s12, s11
	v_lshl_add_u64 v[60:61], s[6:7], 0, v[2:3]
	s_cmpk_lt_i32 s13, 0x3000
	s_waitcnt vmcnt(7)
	v_mul_f32_e32 v2, v26, v65
	v_mul_f32_e32 v3, v27, v4
	v_mul_f32_e32 v4, v28, v66
	v_mul_f32_e32 v5, v29, v5
	s_waitcnt vmcnt(6)
	v_mul_f32_e32 v26, v30, v59
	v_mul_f32_e32 v27, v31, v62
	v_mul_f32_e32 v28, v32, v63
	v_mul_f32_e32 v29, v33, v64
	s_waitcnt vmcnt(5)
	v_fmac_f32_e32 v2, v15, v34
	v_fmac_f32_e32 v3, v16, v35
	v_fmac_f32_e32 v4, v17, v36
	v_fmac_f32_e32 v5, v18, v37
	s_waitcnt vmcnt(4)
	v_fmac_f32_e32 v26, v11, v38
	v_fmac_f32_e32 v27, v12, v39
	v_fmac_f32_e32 v28, v13, v40
	v_fmac_f32_e32 v29, v14, v41
	s_waitcnt vmcnt(3)
	v_fmac_f32_e32 v2, v22, v42
	v_fmac_f32_e32 v3, v23, v43
	v_fmac_f32_e32 v4, v24, v44
	v_fmac_f32_e32 v5, v25, v45
	s_waitcnt vmcnt(2)
	v_fmac_f32_e32 v26, v10, v46
	v_fmac_f32_e32 v27, v19, v47
	v_fmac_f32_e32 v28, v20, v48
	v_fmac_f32_e32 v29, v21, v49
	s_waitcnt vmcnt(1)
	v_add_f32_e32 v2, v50, v2
	v_add_f32_e32 v3, v51, v3
	v_add_f32_e32 v4, v52, v4
	v_add_f32_e32 v5, v53, v5
	s_waitcnt vmcnt(0)
	v_add_f32_e32 v10, v54, v26
	v_add_f32_e32 v11, v55, v27
	v_add_f32_e32 v12, v56, v28
	v_add_f32_e32 v13, v57, v29
	v_cvt_pk_bf16_f32 v2, v2, s0
	v_cvt_pk_bf16_f32 v3, v3, s0
	v_cvt_pk_bf16_f32 v4, v4, s0
	v_cvt_pk_bf16_f32 v5, v5, s0
	v_cvt_pk_bf16_f32 v10, v10, s0
	v_cvt_pk_bf16_f32 v11, v11, s0
	v_cvt_pk_bf16_f32 v12, v12, s0
	v_cvt_pk_bf16_f32 v13, v13, s0
	ds_write_b16 v9, v2 offset:576
	ds_write_b16 v9, v3 offset:720
	ds_write_b16 v9, v4 offset:864
	ds_write_b16 v9, v5 offset:1008
	ds_write_b16 v9, v10
	ds_write_b16 v9, v11 offset:144
	ds_write_b16 v9, v12 offset:288
	ds_write_b16 v9, v13 offset:432
	s_waitcnt lgkmcnt(0)
	s_barrier
	v_ashrrev_i32_e32 v59, 31, v58
	ds_read_b128 v[2:5], v8
	v_lshlrev_b64 v[10:11], s87, v[58:59]
	v_lshl_add_u64 v[10:11], v[10:11], 1, v[60:61]
	v_lshl_add_u64 v[10:11], s[82:83], 1, v[10:11]
	v_lshl_add_u64 v[10:11], v[10:11], 0, v[0:1]
	s_waitcnt lgkmcnt(0)
	global_store_dwordx4 v[10:11], v[2:5], off
	s_barrier
	s_cbranch_scc0 .LBB0_274
.LBB0_270:
	s_ashr_i32 s6, s13, 31
	s_lshr_b32 s6, s6, 23
	s_add_i32 s6, s13, s6
	s_ashr_i32 s6, s6, 9
	s_lshl_b32 s14, s6, 15
	v_readlane_b32 s8, v228, 6
	s_sub_i32 s7, s12, s14
	v_readlane_b32 s9, v228, 7
	s_lshl_b32 s6, s6, 6
	v_add_u32_e32 v26, s7, v7
	v_mov_b64_e32 v[2:3], s[8:9]
	s_movk_i32 s7, 0xc00
	v_mad_i64_i32 v[2:3], s[8:9], v26, s7, v[2:3]
	s_ashr_i32 s7, s6, 31
	v_lshl_add_u64 v[2:3], s[6:7], 1, v[2:3]
	v_lshlrev_b32_e32 v0, 1, v6
	v_lshl_add_u64 v[2:3], v[2:3], 0, v[0:1]
	global_load_dwordx4 v[2:5], v[2:3], off
	v_and_b32_e32 v19, s18, v26
	v_cmp_lt_i32_e32 vcc, 0, v19
	v_mov_b32_e32 v10, 0
	v_mov_b32_e32 v11, 0
	v_mov_b32_e32 v12, 0
	v_mov_b32_e32 v13, 0
	v_mov_b32_e32 v14, 0
	v_mov_b32_e32 v15, 0
	v_mov_b32_e32 v16, 0
	v_mov_b32_e32 v17, 0
	v_mov_b32_e32 v18, 0
	v_mov_b32_e32 v230, 0
	v_mov_b32_e32 v231, 0
	v_mov_b32_e32 v232, 0
	v_mov_b32_e32 v233, 0
	v_mov_b32_e32 v234, 0
	v_mov_b32_e32 v235, 0
	v_mov_b32_e32 v236, 0
	v_mov_b32_e32 v237, 0
	s_and_saveexec_b64 s[8:9], vcc
	s_cbranch_execz .LBB0_272
	v_readlane_b32 s16, v228, 6
	v_readlane_b32 s17, v228, 7
	v_add_u32_e32 v11, -1, v26
	s_movk_i32 s15, 0xc00
	v_mov_b64_e32 v[12:13], s[16:17]
	v_mad_i64_i32 v[12:13], s[16:17], v11, s15, v[12:13]
	v_lshl_add_u64 v[12:13], s[6:7], 1, v[12:13]
	v_lshl_add_u64 v[12:13], v[12:13], 0, v[0:1]
	global_load_dwordx4 v[230:233], v[12:13], off
.LBB0_272:
	s_or_b64 exec, exec, s[8:9]
	s_sub_i32 s14, 0, s14
	v_cmp_gt_i32_e32 vcc, s18, v19
	v_mov_b32_e32 v19, 0
	v_mov_b32_e32 v20, 0
	v_mov_b32_e32 v21, 0
	v_mov_b32_e32 v22, 0
	v_mov_b32_e32 v23, 0
	v_mov_b32_e32 v24, 0
	v_mov_b32_e32 v25, 0
	s_and_saveexec_b64 s[8:9], vcc
	s_cbranch_execz .LBB0_269
	v_readlane_b32 s16, v228, 6
	v_readlane_b32 s17, v228, 7
	v_add_u32_e32 v10, 1, v26
	s_movk_i32 s15, 0xc00
	v_mov_b64_e32 v[20:21], s[16:17]
	v_mad_i64_i32 v[20:21], s[16:17], v10, s15, v[20:21]
	v_lshl_add_u64 v[20:21], s[6:7], 1, v[20:21]
	v_lshl_add_u64 v[20:21], v[20:21], 0, v[0:1]
	global_load_dwordx4 v[234:237], v[20:21], off
	s_branch .LBB0_269

; DI float bf2f(bf16 b) { return __uint_as_float(((unsigned)b) << 16); }
; DI void phase_gdn_c1(const Ctx& c) {
;     ...
;           const int i = hw * 16 + (lane >> 4) * 4 + r, jj = j * 16 + (lane & 15);
;           const float dec = (i >= jj) ? __expf(gcs[i] - gcs[jj]) : 0.f;
;           Am[i * 68 + jj] = (i > jj) ? bs[i] * kk[j][r] * dec : 0.f;
;           CAQK[(size_t)item * 4096 + i * 64 + jj] = f2bf((i >= jj) ? qk[j][r] * dec : 0.f);
;         }
;     }
;     __syncthreads();
;     {
;       float sol[64];
;       const bf16* src = (ht < 128) ? GV : GK;
;       const int cc = ht & 127;
; #pragma unroll
;       for (int i = 0; i < 64; ++i) {
;         float v = bf2f(src[(size_t)(tokb + pos(i)) * 512 + h * 128 + cc]) * bs[i];
;         if (ht >= 128) v *= __expf(gcs[i]);
;         sol[i] = v;
;       }
.LBB0_399:
	s_or_b64 exec, exec, s[38:39]
	ds_write_b32 v78, v2 offset:35008
	v_mul_f32_e32 v2, v5, v3
	v_xad_u32 v4, v82, -1, s86
	v_cvt_pk_bf16_f32 v2, v2, s0
	v_cndmask_b32_e64 v4, v4, v82, s[90:91]
	v_cndmask_b32_e64 v2, v2, 0, s[46:47]
	v_add_u32_e32 v4, v4, v81
	global_store_short v[28:29], v2, off offset:96
	v_lshlrev_b32_e32 v2, 1, v83
	v_mov_b32_e32 v3, v1
	v_ashrrev_i32_e32 v5, 31, v4
	v_lshl_add_u64 v[2:3], v[34:35], 0, v[2:3]
	v_lshlrev_b64 v[4:5], 10, v[4:5]
	v_lshl_add_u64 v[4:5], v[2:3], 0, v[4:5]
	s_waitcnt lgkmcnt(0)
	s_barrier
	global_load_ushort v4, v[4:5], off
	v_or_b32_e32 v232, 1, v82
	v_xad_u32 v233, v82, -2, s86
	v_cndmask_b32_e64 v232, v233, v232, s[90:91]
	v_add_u32_e32 v230, v232, v81
	v_ashrrev_i32_e32 v231, 31, v230
	v_lshlrev_b64 v[230:231], 10, v[230:231]
	v_lshl_add_u64 v[230:231], v[2:3], 0, v[230:231]
	global_load_ushort v5, v[230:231], off
	v_or_b32_e32 v232, 2, v82
	v_xad_u32 v233, v82, -3, s86
	v_cndmask_b32_e64 v232, v233, v232, s[90:91]
	v_add_u32_e32 v230, v232, v81
	v_ashrrev_i32_e32 v231, 31, v230
	v_lshlrev_b64 v[230:231], 10, v[230:231]
	v_lshl_add_u64 v[230:231], v[2:3], 0, v[230:231]
	global_load_ushort v6, v[230:231], off
	v_or_b32_e32 v232, 3, v82
	v_xad_u32 v233, v82, -4, s86
	v_cndmask_b32_e64 v232, v233, v232, s[90:91]
	v_add_u32_e32 v230, v232, v81
	v_ashrrev_i32_e32 v231, 31, v230
	v_lshlrev_b64 v[230:231], 10, v[230:231]
	v_lshl_add_u64 v[230:231], v[2:3], 0, v[230:231]
	global_load_ushort v7, v[230:231], off
	v_or_b32_e32 v232, 4, v82
	v_xad_u32 v233, v82, -5, s86
	v_cndmask_b32_e64 v232, v233, v232, s[90:91]
	v_add_u32_e32 v230, v232, v81
	v_ashrrev_i32_e32 v231, 31, v230
	v_lshlrev_b64 v[230:231], 10, v[230:231]
	v_lshl_add_u64 v[230:231], v[2:3], 0, v[230:231]
	global_load_ushort v8, v[230:231], off
	v_or_b32_e32 v232, 5, v82
	v_xad_u32 v233, v82, -6, s86
	v_cndmask_b32_e64 v232, v233, v232, s[90:91]
	v_add_u32_e32 v230, v232, v81
	v_ashrrev_i32_e32 v231, 31, v230
	v_lshlrev_b64 v[230:231], 10, v[230:231]
	v_lshl_add_u64 v[230:231], v[2:3], 0, v[230:231]
	global_load_ushort v9, v[230:231], off
	v_or_b32_e32 v232, 6, v82
	v_xad_u32 v233, v82, -7, s86
	v_cndmask_b32_e64 v232, v233, v232, s[90:91]
	v_add_u32_e32 v230, v232, v81
	v_ashrrev_i32_e32 v231, 31, v230
	v_lshlrev_b64 v[230:231], 10, v[230:231]
	v_lshl_add_u64 v[230:231], v[2:3], 0, v[230:231]
	global_load_ushort v10, v[230:231], off
	v_or_b32_e32 v232, 7, v82
	v_xad_u32 v233, v82, -8, s86
	v_cndmask_b32_e64 v232, v233, v232, s[90:91]
	v_add_u32_e32 v230, v232, v81
	v_ashrrev_i32_e32 v231, 31, v230
	v_lshlrev_b64 v[230:231], 10, v[230:231]
	v_lshl_add_u64 v[230:231], v[2:3], 0, v[230:231]
	global_load_ushort v12, v[230:231], off
	v_or_b32_e32 v232, 8, v82
	v_xad_u32 v233, v82, -9, s86
	v_cndmask_b32_e64 v232, v233, v232, s[90:91]
	v_add_u32_e32 v230, v232, v81
	v_ashrrev_i32_e32 v231, 31, v230
	v_lshlrev_b64 v[230:231], 10, v[230:231]
	v_lshl_add_u64 v[230:231], v[2:3], 0, v[230:231]
	global_load_ushort v13, v[230:231], off
	v_or_b32_e32 v232, 9, v82
	v_xad_u32 v233, v82, -10, s86
	v_cndmask_b32_e64 v232, v233, v232, s[90:91]
	v_add_u32_e32 v230, v232, v81
	v_ashrrev_i32_e32 v231, 31, v230
	v_lshlrev_b64 v[230:231], 10, v[230:231]
	v_lshl_add_u64 v[230:231], v[2:3], 0, v[230:231]
	global_load_ushort v15, v[230:231], off
	v_or_b32_e32 v232, 10, v82
	v_xad_u32 v233, v82, -11, s86
	v_cndmask_b32_e64 v232, v233, v232, s[90:91]
	v_add_u32_e32 v230, v232, v81
	v_ashrrev_i32_e32 v231, 31, v230
	v_lshlrev_b64 v[230:231], 10, v[230:231]
	v_lshl_add_u64 v[230:231], v[2:3], 0, v[230:231]
	global_load_ushort v14, v[230:231], off
	v_or_b32_e32 v232, 11, v82
	v_xad_u32 v233, v82, -12, s86
	v_cndmask_b32_e64 v232, v233, v232, s[90:91]
	v_add_u32_e32 v230, v232, v81
	v_ashrrev_i32_e32 v231, 31, v230
	v_lshlrev_b64 v[230:231], 10, v[230:231]
	v_lshl_add_u64 v[230:231], v[2:3], 0, v[230:231]
	global_load_ushort v109, v[230:231], off
	v_or_b32_e32 v232, 12, v82
	v_xad_u32 v233, v82, -13, s86
	v_cndmask_b32_e64 v232, v233, v232, s[90:91]
	v_add_u32_e32 v230, v232, v81
	v_ashrrev_i32_e32 v231, 31, v230
	v_lshlrev_b64 v[230:231], 10, v[230:231]
	v_lshl_add_u64 v[230:231], v[2:3], 0, v[230:231]
	global_load_ushort v17, v[230:231], off
	v_or_b32_e32 v232, 13, v82
	v_xad_u32 v233, v82, -14, s86
	v_cndmask_b32_e64 v232, v233, v232, s[90:91]
	v_add_u32_e32 v230, v232, v81
	v_ashrrev_i32_e32 v231, 31, v230
	v_lshlrev_b64 v[230:231], 10, v[230:231]
	v_lshl_add_u64 v[230:231], v[2:3], 0, v[230:231]
	global_load_ushort v108, v[230:231], off
	v_or_b32_e32 v232, 14, v82
	v_xad_u32 v233, v82, -15, s86
	v_cndmask_b32_e64 v232, v233, v232, s[90:91]
	v_add_u32_e32 v230, v232, v81
	v_ashrrev_i32_e32 v231, 31, v230
	v_lshlrev_b64 v[230:231], 10, v[230:231]
	v_lshl_add_u64 v[230:231], v[2:3], 0, v[230:231]
	global_load_ushort v18, v[230:231], off
	v_or_b32_e32 v232, 15, v82
	v_xad_u32 v233, v82, -16, s86
	v_cndmask_b32_e64 v232, v233, v232, s[90:91]
	v_add_u32_e32 v230, v232, v81
	v_ashrrev_i32_e32 v231, 31, v230
	v_lshlrev_b64 v[230:231], 10, v[230:231]
	v_lshl_add_u64 v[230:231], v[2:3], 0, v[230:231]
	global_load_ushort v19, v[230:231], off
	v_or_b32_e32 v232, 16, v82
	v_xor_b32_e32 v233, 0xffffffef, v82
	v_add_u32_e32 v233, s86, v233
	v_cndmask_b32_e64 v232, v233, v232, s[90:91]
	v_add_u32_e32 v230, v232, v81
	v_ashrrev_i32_e32 v231, 31, v230
	v_lshlrev_b64 v[230:231], 10, v[230:231]
	v_lshl_add_u64 v[230:231], v[2:3], 0, v[230:231]
	global_load_ushort v21, v[230:231], off
	v_or_b32_e32 v232, 17, v82
	v_xor_b32_e32 v233, 0xffffffee, v82
	v_add_u32_e32 v233, s86, v233
	v_cndmask_b32_e64 v232, v233, v232, s[90:91]
	v_add_u32_e32 v230, v232, v81
; DI float bf2f(bf16 b) { return __uint_as_float(((unsigned)b) << 16); }
; DI void phase_gdn_c1(const Ctx& c) {
;     ...
;       const bf16* src = (ht < 128) ? GV : GK;
;       const int cc = ht & 127;
; #pragma unroll
;       for (int i = 0; i < 64; ++i) {
;         float v = bf2f(src[(size_t)(tokb + pos(i)) * 512 + h * 128 + cc]) * bs[i];
	v_ashrrev_i32_e32 v231, 31, v230
	v_lshlrev_b64 v[230:231], 10, v[230:231]
	v_lshl_add_u64 v[230:231], v[2:3], 0, v[230:231]
	global_load_ushort v22, v[230:231], off
	v_or_b32_e32 v232, 18, v82
	v_xor_b32_e32 v233, 0xffffffed, v82
	v_add_u32_e32 v233, s86, v233
	v_cndmask_b32_e64 v232, v233, v232, s[90:91]
	v_add_u32_e32 v230, v232, v81
	v_ashrrev_i32_e32 v231, 31, v230
	v_lshlrev_b64 v[230:231], 10, v[230:231]
	v_lshl_add_u64 v[230:231], v[2:3], 0, v[230:231]
	global_load_ushort v23, v[230:231], off
	v_or_b32_e32 v232, 19, v82
	v_xor_b32_e32 v233, 0xffffffec, v82
	v_add_u32_e32 v233, s86, v233
	v_cndmask_b32_e64 v232, v233, v232, s[90:91]
	v_add_u32_e32 v230, v232, v81
	v_ashrrev_i32_e32 v231, 31, v230
	v_lshlrev_b64 v[230:231], 10, v[230:231]
	v_lshl_add_u64 v[230:231], v[2:3], 0, v[230:231]
	global_load_ushort v25, v[230:231], off
	v_or_b32_e32 v232, 20, v82
	v_xor_b32_e32 v233, 0xffffffeb, v82
	v_add_u32_e32 v233, s86, v233
	v_cndmask_b32_e64 v232, v233, v232, s[90:91]
	v_add_u32_e32 v230, v232, v81
	v_ashrrev_i32_e32 v231, 31, v230
	v_lshlrev_b64 v[230:231], 10, v[230:231]
	v_lshl_add_u64 v[230:231], v[2:3], 0, v[230:231]
	global_load_ushort v26, v[230:231], off
	v_or_b32_e32 v232, 21, v82
	v_xor_b32_e32 v233, 0xffffffea, v82
	v_add_u32_e32 v233, s86, v233
	v_cndmask_b32_e64 v232, v233, v232, s[90:91]
	v_add_u32_e32 v230, v232, v81
	v_ashrrev_i32_e32 v231, 31, v230
	v_lshlrev_b64 v[230:231], 10, v[230:231]
	v_lshl_add_u64 v[230:231], v[2:3], 0, v[230:231]
	global_load_ushort v28, v[230:231], off
	v_or_b32_e32 v232, 22, v82
	v_xor_b32_e32 v233, 0xffffffe9, v82
	v_add_u32_e32 v233, s86, v233
	v_cndmask_b32_e64 v232, v233, v232, s[90:91]
	v_add_u32_e32 v230, v232, v81
	v_ashrrev_i32_e32 v231, 31, v230
	v_lshlrev_b64 v[230:231], 10, v[230:231]
	v_lshl_add_u64 v[230:231], v[2:3], 0, v[230:231]
	global_load_ushort v29, v[230:231], off
	v_or_b32_e32 v232, 23, v82
	v_xor_b32_e32 v233, 0xffffffe8, v82
	v_add_u32_e32 v233, s86, v233
	v_cndmask_b32_e64 v232, v233, v232, s[90:91]
	v_add_u32_e32 v230, v232, v81
	v_ashrrev_i32_e32 v231, 31, v230
	v_lshlrev_b64 v[230:231], 10, v[230:231]
	v_lshl_add_u64 v[230:231], v[2:3], 0, v[230:231]
	global_load_ushort v31, v[230:231], off
	v_or_b32_e32 v232, 24, v82
	v_xor_b32_e32 v233, 0xffffffe7, v82
	v_add_u32_e32 v233, s86, v233
	v_cndmask_b32_e64 v232, v233, v232, s[90:91]
	v_add_u32_e32 v230, v232, v81
	v_ashrrev_i32_e32 v231, 31, v230
	v_lshlrev_b64 v[230:231], 10, v[230:231]
	v_lshl_add_u64 v[230:231], v[2:3], 0, v[230:231]
	global_load_ushort v32, v[230:231], off
	v_or_b32_e32 v232, 25, v82
	v_xor_b32_e32 v233, 0xffffffe6, v82
	v_add_u32_e32 v233, s86, v233
	v_cndmask_b32_e64 v232, v233, v232, s[90:91]
	v_add_u32_e32 v230, v232, v81
	v_ashrrev_i32_e32 v231, 31, v230
	v_lshlrev_b64 v[230:231], 10, v[230:231]
	v_lshl_add_u64 v[230:231], v[2:3], 0, v[230:231]
	global_load_ushort v43, v[230:231], off
	v_or_b32_e32 v232, 26, v82
	v_xor_b32_e32 v233, 0xffffffe5, v82
	v_add_u32_e32 v233, s86, v233
	v_cndmask_b32_e64 v232, v233, v232, s[90:91]
	v_add_u32_e32 v230, v232, v81
	v_ashrrev_i32_e32 v231, 31, v230
	v_lshlrev_b64 v[230:231], 10, v[230:231]
	v_lshl_add_u64 v[230:231], v[2:3], 0, v[230:231]
	global_load_ushort v47, v[230:231], off
	v_or_b32_e32 v232, 27, v82
	v_xor_b32_e32 v233, 0xffffffe4, v82
	v_add_u32_e32 v233, s86, v233
	v_cndmask_b32_e64 v232, v233, v232, s[90:91]
	v_add_u32_e32 v230, v232, v81
	v_ashrrev_i32_e32 v231, 31, v230
	v_lshlrev_b64 v[230:231], 10, v[230:231]
	v_lshl_add_u64 v[230:231], v[2:3], 0, v[230:231]
	global_load_ushort v50, v[230:231], off
	v_or_b32_e32 v232, 28, v82
	v_xor_b32_e32 v233, 0xffffffe3, v82
	v_add_u32_e32 v233, s86, v233
	v_cndmask_b32_e64 v232, v233, v232, s[90:91]
	v_add_u32_e32 v230, v232, v81
	v_ashrrev_i32_e32 v231, 31, v230
	v_lshlrev_b64 v[230:231], 10, v[230:231]
	v_lshl_add_u64 v[230:231], v[2:3], 0, v[230:231]
	global_load_ushort v52, v[230:231], off
	v_or_b32_e32 v232, 29, v82
	v_xor_b32_e32 v233, 0xffffffe2, v82
	v_add_u32_e32 v233, s86, v233
	v_cndmask_b32_e64 v232, v233, v232, s[90:91]
	v_add_u32_e32 v230, v232, v81
	v_ashrrev_i32_e32 v231, 31, v230
	v_lshlrev_b64 v[230:231], 10, v[230:231]
	v_lshl_add_u64 v[230:231], v[2:3], 0, v[230:231]
	global_load_ushort v107, v[230:231], off
	v_or_b32_e32 v232, 30, v82
	v_xor_b32_e32 v233, 0xffffffe1, v82
	v_add_u32_e32 v233, s86, v233
	v_cndmask_b32_e64 v232, v233, v232, s[90:91]
	v_add_u32_e32 v230, v232, v81
	v_ashrrev_i32_e32 v231, 31, v230
	v_lshlrev_b64 v[230:231], 10, v[230:231]
	v_lshl_add_u64 v[230:231], v[2:3], 0, v[230:231]
	global_load_ushort v106, v[230:231], off
	v_or_b32_e32 v232, 31, v82
	v_xor_b32_e32 v233, 0xffffffe0, v82
	v_add_u32_e32 v233, s86, v233
	v_cndmask_b32_e64 v232, v233, v232, s[90:91]
	v_add_u32_e32 v230, v232, v81
	v_ashrrev_i32_e32 v231, 31, v230
	v_lshlrev_b64 v[230:231], 10, v[230:231]
	v_lshl_add_u64 v[230:231], v[2:3], 0, v[230:231]
	global_load_ushort v84, v[230:231], off
	s_waitcnt vmcnt(30)
; DI float bf2f(bf16 b) { return __uint_as_float(((unsigned)b) << 16); }
; DI void phase_gdn_c1(const Ctx& c) {
;     ...
;       const bf16* src = (ht < 128) ? GV : GK;
;       const int cc = ht & 127;
; #pragma unroll
;       for (int i = 0; i < 64; ++i) {
;         float v = bf2f(src[(size_t)(tokb + pos(i)) * 512 + h * 128 + cc]) * bs[i];
	v_or_b32_e32 v232, 32, v82
	v_xor_b32_e32 v233, 0xffffffdf, v82
	v_add_u32_e32 v233, s86, v233
	v_cndmask_b32_e64 v232, v233, v232, s[90:91]
	v_add_u32_e32 v230, v232, v81
	v_ashrrev_i32_e32 v231, 31, v230
	v_lshlrev_b64 v[230:231], 10, v[230:231]
	v_lshl_add_u64 v[230:231], v[2:3], 0, v[230:231]
	global_load_ushort v86, v[230:231], off
	v_or_b32_e32 v232, 33, v82
	v_xor_b32_e32 v233, 0xffffffde, v82
	v_add_u32_e32 v233, s86, v233
	v_cndmask_b32_e64 v232, v233, v232, s[90:91]
	v_add_u32_e32 v230, v232, v81
	v_ashrrev_i32_e32 v231, 31, v230
	v_lshlrev_b64 v[230:231], 10, v[230:231]
	v_lshl_add_u64 v[230:231], v[2:3], 0, v[230:231]
	global_load_ushort v88, v[230:231], off
	v_or_b32_e32 v232, 34, v82
	v_xor_b32_e32 v233, 0xffffffdd, v82
	v_add_u32_e32 v233, s86, v233
	v_cndmask_b32_e64 v232, v233, v232, s[90:91]
	v_add_u32_e32 v230, v232, v81
	v_ashrrev_i32_e32 v231, 31, v230
	v_lshlrev_b64 v[230:231], 10, v[230:231]
	v_lshl_add_u64 v[230:231], v[2:3], 0, v[230:231]
	global_load_ushort v90, v[230:231], off
	v_or_b32_e32 v232, 35, v82
	v_xor_b32_e32 v233, 0xffffffdc, v82
	v_add_u32_e32 v233, s86, v233
	v_cndmask_b32_e64 v232, v233, v232, s[90:91]
	v_add_u32_e32 v230, v232, v81
	v_ashrrev_i32_e32 v231, 31, v230
	v_lshlrev_b64 v[230:231], 10, v[230:231]
	v_lshl_add_u64 v[230:231], v[2:3], 0, v[230:231]
	global_load_ushort v92, v[230:231], off
	v_or_b32_e32 v232, 36, v82
	v_xor_b32_e32 v233, 0xffffffdb, v82
	v_add_u32_e32 v233, s86, v233
	v_cndmask_b32_e64 v232, v233, v232, s[90:91]
	v_add_u32_e32 v230, v232, v81
	v_ashrrev_i32_e32 v231, 31, v230
	v_lshlrev_b64 v[230:231], 10, v[230:231]
	v_lshl_add_u64 v[230:231], v[2:3], 0, v[230:231]
	global_load_ushort v94, v[230:231], off
	v_or_b32_e32 v232, 37, v82
	v_xor_b32_e32 v233, 0xffffffda, v82
	v_add_u32_e32 v233, s86, v233
	v_cndmask_b32_e64 v232, v233, v232, s[90:91]
	v_add_u32_e32 v230, v232, v81
	v_ashrrev_i32_e32 v231, 31, v230
	v_lshlrev_b64 v[230:231], 10, v[230:231]
	v_lshl_add_u64 v[230:231], v[2:3], 0, v[230:231]
	global_load_ushort v96, v[230:231], off
	v_or_b32_e32 v232, 38, v82
	v_xor_b32_e32 v233, 0xffffffd9, v82
	v_add_u32_e32 v233, s86, v233
	v_cndmask_b32_e64 v232, v233, v232, s[90:91]
	v_add_u32_e32 v230, v232, v81
	v_ashrrev_i32_e32 v231, 31, v230
	v_lshlrev_b64 v[230:231], 10, v[230:231]
	v_lshl_add_u64 v[230:231], v[2:3], 0, v[230:231]
	global_load_ushort v98, v[230:231], off
	v_or_b32_e32 v232, 39, v82
	v_xor_b32_e32 v233, 0xffffffd8, v82
	v_add_u32_e32 v233, s86, v233
	v_cndmask_b32_e64 v232, v233, v232, s[90:91]
	v_add_u32_e32 v230, v232, v81
	v_ashrrev_i32_e32 v231, 31, v230
	v_lshlrev_b64 v[230:231], 10, v[230:231]
	v_lshl_add_u64 v[230:231], v[2:3], 0, v[230:231]
	global_load_ushort v100, v[230:231], off
	v_or_b32_e32 v232, 40, v82
	v_xor_b32_e32 v233, 0xffffffd7, v82
	v_add_u32_e32 v233, s86, v233
	v_cndmask_b32_e64 v232, v233, v232, s[90:91]
	v_add_u32_e32 v230, v232, v81
	v_ashrrev_i32_e32 v231, 31, v230
	v_lshlrev_b64 v[230:231], 10, v[230:231]
	v_lshl_add_u64 v[230:231], v[2:3], 0, v[230:231]
	global_load_ushort v103, v[230:231], off
	v_or_b32_e32 v232, 41, v82
	v_xor_b32_e32 v233, 0xffffffd6, v82
	v_add_u32_e32 v233, s86, v233
	v_cndmask_b32_e64 v232, v233, v232, s[90:91]
	v_add_u32_e32 v230, v232, v81
	v_ashrrev_i32_e32 v231, 31, v230
	v_lshlrev_b64 v[230:231], 10, v[230:231]
	v_lshl_add_u64 v[230:231], v[2:3], 0, v[230:231]
	global_load_ushort v105, v[230:231], off
	v_or_b32_e32 v232, 42, v82
	v_xor_b32_e32 v233, 0xffffffd5, v82
	v_add_u32_e32 v233, s86, v233
	v_cndmask_b32_e64 v232, v233, v232, s[90:91]
	v_add_u32_e32 v230, v232, v81
	v_ashrrev_i32_e32 v231, 31, v230
	v_lshlrev_b64 v[230:231], 10, v[230:231]
	v_lshl_add_u64 v[230:231], v[2:3], 0, v[230:231]
	global_load_ushort v104, v[230:231], off
	v_or_b32_e32 v232, 43, v82
	v_xor_b32_e32 v233, 0xffffffd4, v82
	v_add_u32_e32 v233, s86, v233
	v_cndmask_b32_e64 v232, v233, v232, s[90:91]
	v_add_u32_e32 v230, v232, v81
	v_ashrrev_i32_e32 v231, 31, v230
	v_lshlrev_b64 v[230:231], 10, v[230:231]
	v_lshl_add_u64 v[230:231], v[2:3], 0, v[230:231]
	global_load_ushort v102, v[230:231], off
	v_or_b32_e32 v232, 44, v82
	v_xor_b32_e32 v233, 0xffffffd3, v82
	v_add_u32_e32 v233, s86, v233
	v_cndmask_b32_e64 v232, v233, v232, s[90:91]
	v_add_u32_e32 v230, v232, v81
	v_ashrrev_i32_e32 v231, 31, v230
	v_lshlrev_b64 v[230:231], 10, v[230:231]
	v_lshl_add_u64 v[230:231], v[2:3], 0, v[230:231]
	global_load_ushort v101, v[230:231], off
	v_or_b32_e32 v232, 45, v82
	v_xor_b32_e32 v233, 0xffffffd2, v82
	v_add_u32_e32 v233, s86, v233
	v_cndmask_b32_e64 v232, v233, v232, s[90:91]
	v_add_u32_e32 v230, v232, v81
	v_ashrrev_i32_e32 v231, 31, v230
	v_lshlrev_b64 v[230:231], 10, v[230:231]
	v_lshl_add_u64 v[230:231], v[2:3], 0, v[230:231]
	global_load_ushort v99, v[230:231], off
	v_or_b32_e32 v232, 46, v82
	v_xor_b32_e32 v233, 0xffffffd1, v82
	v_add_u32_e32 v233, s86, v233
	v_cndmask_b32_e64 v232, v233, v232, s[90:91]
	v_add_u32_e32 v230, v232, v81
	v_ashrrev_i32_e32 v231, 31, v230
	v_lshlrev_b64 v[230:231], 10, v[230:231]
	v_lshl_add_u64 v[230:231], v[2:3], 0, v[230:231]
	global_load_ushort v97, v[230:231], off
	v_or_b32_e32 v232, 47, v82
	v_xor_b32_e32 v233, 0xffffffd0, v82
	v_add_u32_e32 v233, s86, v233
	v_cndmask_b32_e64 v232, v233, v232, s[90:91]
	v_add_u32_e32 v230, v232, v81
	v_ashrrev_i32_e32 v231, 31, v230
	v_lshlrev_b64 v[230:231], 10, v[230:231]
	v_lshl_add_u64 v[230:231], v[2:3], 0, v[230:231]
	global_load_ushort v95, v[230:231], off
	v_or_b32_e32 v232, 48, v82
	v_xor_b32_e32 v233, 0xffffffcf, v82
	v_add_u32_e32 v233, s86, v233
	v_cndmask_b32_e64 v232, v233, v232, s[90:91]
	v_add_u32_e32 v230, v232, v81
	v_ashrrev_i32_e32 v231, 31, v230
; DI float bf2f(bf16 b) { return __uint_as_float(((unsigned)b) << 16); }
; DI void phase_gdn_c1(const Ctx& c) {
;     ...
;       const bf16* src = (ht < 128) ? GV : GK;
;       const int cc = ht & 127;
; #pragma unroll
;       for (int i = 0; i < 64; ++i) {
;         float v = bf2f(src[(size_t)(tokb + pos(i)) * 512 + h * 128 + cc]) * bs[i];
;         if (ht >= 128) v *= __expf(gcs[i]);
;         sol[i] = v;
	v_lshlrev_b64 v[230:231], 10, v[230:231]
	v_lshl_add_u64 v[230:231], v[2:3], 0, v[230:231]
	global_load_ushort v93, v[230:231], off
	v_or_b32_e32 v232, 49, v82
	v_xor_b32_e32 v233, 0xffffffce, v82
	v_add_u32_e32 v233, s86, v233
	v_cndmask_b32_e64 v232, v233, v232, s[90:91]
	v_add_u32_e32 v230, v232, v81
	v_ashrrev_i32_e32 v231, 31, v230
	v_lshlrev_b64 v[230:231], 10, v[230:231]
	v_lshl_add_u64 v[230:231], v[2:3], 0, v[230:231]
	global_load_ushort v91, v[230:231], off
	v_or_b32_e32 v232, 50, v82
	v_xor_b32_e32 v233, 0xffffffcd, v82
	v_add_u32_e32 v233, s86, v233
	v_cndmask_b32_e64 v232, v233, v232, s[90:91]
	v_add_u32_e32 v230, v232, v81
	v_ashrrev_i32_e32 v231, 31, v230
	v_lshlrev_b64 v[230:231], 10, v[230:231]
	v_lshl_add_u64 v[230:231], v[2:3], 0, v[230:231]
	global_load_ushort v89, v[230:231], off
	v_or_b32_e32 v232, 51, v82
	v_xor_b32_e32 v233, 0xffffffcc, v82
	v_add_u32_e32 v233, s86, v233
	v_cndmask_b32_e64 v232, v233, v232, s[90:91]
	v_add_u32_e32 v230, v232, v81
	v_ashrrev_i32_e32 v231, 31, v230
	v_lshlrev_b64 v[230:231], 10, v[230:231]
	v_lshl_add_u64 v[230:231], v[2:3], 0, v[230:231]
	global_load_ushort v87, v[230:231], off
	v_or_b32_e32 v232, 52, v82
	v_xor_b32_e32 v233, 0xffffffcb, v82
	v_add_u32_e32 v233, s86, v233
	v_cndmask_b32_e64 v232, v233, v232, s[90:91]
	v_add_u32_e32 v230, v232, v81
	v_ashrrev_i32_e32 v231, 31, v230
	v_lshlrev_b64 v[230:231], 10, v[230:231]
	v_lshl_add_u64 v[230:231], v[2:3], 0, v[230:231]
	global_load_ushort v85, v[230:231], off
	v_or_b32_e32 v232, 53, v82
	v_xor_b32_e32 v233, 0xffffffca, v82
	v_add_u32_e32 v233, s86, v233
	v_cndmask_b32_e64 v232, v233, v232, s[90:91]
	v_add_u32_e32 v230, v232, v81
	v_ashrrev_i32_e32 v231, 31, v230
	v_lshlrev_b64 v[230:231], 10, v[230:231]
	v_lshl_add_u64 v[230:231], v[2:3], 0, v[230:231]
	global_load_ushort v83, v[230:231], off
	v_or_b32_e32 v232, 54, v82
	v_xor_b32_e32 v233, 0xffffffc9, v82
	v_add_u32_e32 v233, s86, v233
	v_cndmask_b32_e64 v232, v233, v232, s[90:91]
	v_add_u32_e32 v230, v232, v81
	v_ashrrev_i32_e32 v231, 31, v230
	v_lshlrev_b64 v[230:231], 10, v[230:231]
	v_lshl_add_u64 v[230:231], v[2:3], 0, v[230:231]
	global_load_ushort v53, v[230:231], off
	v_or_b32_e32 v232, 55, v82
	v_xor_b32_e32 v233, 0xffffffc8, v82
	v_add_u32_e32 v233, s86, v233
	v_cndmask_b32_e64 v232, v233, v232, s[90:91]
	v_add_u32_e32 v230, v232, v81
	v_ashrrev_i32_e32 v231, 31, v230
	v_lshlrev_b64 v[230:231], 10, v[230:231]
	v_lshl_add_u64 v[230:231], v[2:3], 0, v[230:231]
	global_load_ushort v51, v[230:231], off
	v_or_b32_e32 v232, 56, v82
	v_xor_b32_e32 v233, 0xffffffc7, v82
	v_add_u32_e32 v233, s86, v233
	v_cndmask_b32_e64 v232, v233, v232, s[90:91]
	v_add_u32_e32 v230, v232, v81
	v_ashrrev_i32_e32 v231, 31, v230
	v_lshlrev_b64 v[230:231], 10, v[230:231]
	v_lshl_add_u64 v[230:231], v[2:3], 0, v[230:231]
	global_load_ushort v45, v[230:231], off
	v_or_b32_e32 v232, 57, v82
	v_xor_b32_e32 v233, 0xffffffc6, v82
	v_add_u32_e32 v233, s86, v233
	v_cndmask_b32_e64 v232, v233, v232, s[90:91]
	v_add_u32_e32 v230, v232, v81
	v_ashrrev_i32_e32 v231, 31, v230
	v_lshlrev_b64 v[230:231], 10, v[230:231]
	v_lshl_add_u64 v[230:231], v[2:3], 0, v[230:231]
	global_load_ushort v33, v[230:231], off
	v_or_b32_e32 v232, 58, v82
	v_xor_b32_e32 v233, 0xffffffc5, v82
	v_add_u32_e32 v233, s86, v233
	v_cndmask_b32_e64 v232, v233, v232, s[90:91]
	v_add_u32_e32 v230, v232, v81
	v_ashrrev_i32_e32 v231, 31, v230
	v_lshlrev_b64 v[230:231], 10, v[230:231]
	v_lshl_add_u64 v[230:231], v[2:3], 0, v[230:231]
	global_load_ushort v30, v[230:231], off
	v_or_b32_e32 v232, 59, v82
	v_xor_b32_e32 v233, 0xffffffc4, v82
	v_add_u32_e32 v233, s86, v233
	v_cndmask_b32_e64 v232, v233, v232, s[90:91]
	v_add_u32_e32 v230, v232, v81
	v_ashrrev_i32_e32 v231, 31, v230
	v_lshlrev_b64 v[230:231], 10, v[230:231]
	v_lshl_add_u64 v[230:231], v[2:3], 0, v[230:231]
	global_load_ushort v27, v[230:231], off
	v_or_b32_e32 v232, 60, v82
	v_xor_b32_e32 v233, 0xffffffc3, v82
	v_add_u32_e32 v233, s86, v233
	v_cndmask_b32_e64 v232, v233, v232, s[90:91]
	v_add_u32_e32 v230, v232, v81
	v_ashrrev_i32_e32 v231, 31, v230
	v_lshlrev_b64 v[230:231], 10, v[230:231]
	v_lshl_add_u64 v[230:231], v[2:3], 0, v[230:231]
	global_load_ushort v24, v[230:231], off
	v_or_b32_e32 v232, 61, v82
	v_xor_b32_e32 v233, 0xffffffc2, v82
	v_add_u32_e32 v233, s86, v233
	v_cndmask_b32_e64 v232, v233, v232, s[90:91]
	v_add_u32_e32 v230, v232, v81
	v_ashrrev_i32_e32 v231, 31, v230
	v_lshlrev_b64 v[230:231], 10, v[230:231]
	v_lshl_add_u64 v[230:231], v[2:3], 0, v[230:231]
	global_load_ushort v20, v[230:231], off
	v_or_b32_e32 v232, 62, v82
	v_xor_b32_e32 v233, 0xffffffc1, v82
	v_add_u32_e32 v233, s86, v233
	v_cndmask_b32_e64 v232, v233, v232, s[90:91]
	v_add_u32_e32 v230, v232, v81
	v_ashrrev_i32_e32 v231, 31, v230
	v_lshlrev_b64 v[230:231], 10, v[230:231]
	v_lshl_add_u64 v[230:231], v[2:3], 0, v[230:231]
	global_load_ushort v16, v[230:231], off
	v_or_b32_e32 v232, 63, v82
	v_xor_b32_e32 v233, 0xffffffc0, v82
	v_add_u32_e32 v233, s86, v233
	v_cndmask_b32_e64 v232, v233, v232, s[90:91]
	v_add_u32_e32 v230, v232, v81
	v_ashrrev_i32_e32 v231, 31, v230
	v_lshlrev_b64 v[230:231], 10, v[230:231]
	v_lshl_add_u64 v[230:231], v[2:3], 0, v[230:231]
	global_load_ushort v11, v[230:231], off
	ds_read_b128 v[234:237], v56 offset:52480
	ds_read_b128 v[238:241], v56 offset:52496
	s_waitcnt vmcnt(32)
	s_waitcnt lgkmcnt(1)
	v_lshlrev_b32_e32 v4, 16, v4
	v_lshlrev_b32_e32 v5, 16, v5
	v_lshlrev_b32_e32 v6, 16, v6
	v_lshlrev_b32_e32 v7, 16, v7
	v_mul_f32_e32 v4, v234, v4
	v_mul_f32_e32 v5, v235, v5
	v_mul_f32_e32 v6, v236, v6
	v_mul_f32_e32 v7, v237, v7
	ds_read_b128 v[234:237], v56 offset:52512
	s_waitcnt lgkmcnt(1)
; DI float bf2f(bf16 b) { return __uint_as_float(((unsigned)b) << 16); }
; DI void phase_gdn_c1(const Ctx& c) {
;     ...
;       for (int i = 0; i < 64; ++i) {
;         float v = bf2f(src[(size_t)(tokb + pos(i)) * 512 + h * 128 + cc]) * bs[i];
;         if (ht >= 128) v *= __expf(gcs[i]);
;         sol[i] = v;
	v_lshlrev_b32_e32 v8, 16, v8
	v_lshlrev_b32_e32 v9, 16, v9
	v_lshlrev_b32_e32 v10, 16, v10
	v_lshlrev_b32_e32 v12, 16, v12
	v_mul_f32_e32 v8, v238, v8
	v_mul_f32_e32 v9, v239, v9
	v_mul_f32_e32 v10, v240, v10
	v_mul_f32_e32 v12, v241, v12
	ds_read_b128 v[238:241], v56 offset:52528
	s_waitcnt lgkmcnt(1)
	v_lshlrev_b32_e32 v13, 16, v13
	v_lshlrev_b32_e32 v15, 16, v15
	v_lshlrev_b32_e32 v14, 16, v14
	v_lshlrev_b32_e32 v109, 16, v109
	v_mul_f32_e32 v13, v234, v13
	v_mul_f32_e32 v15, v235, v15
	v_mul_f32_e32 v14, v236, v14
	v_mul_f32_e32 v109, v237, v109
	ds_read_b128 v[234:237], v56 offset:52544
	s_waitcnt lgkmcnt(1)
	v_lshlrev_b32_e32 v17, 16, v17
	v_lshlrev_b32_e32 v108, 16, v108
	v_lshlrev_b32_e32 v18, 16, v18
	v_lshlrev_b32_e32 v19, 16, v19
	v_mul_f32_e32 v17, v238, v17
	v_mul_f32_e32 v108, v239, v108
	v_mul_f32_e32 v18, v240, v18
	v_mul_f32_e32 v19, v241, v19
	ds_read_b128 v[238:241], v56 offset:52560
	s_waitcnt lgkmcnt(1)
	v_lshlrev_b32_e32 v21, 16, v21
	v_lshlrev_b32_e32 v22, 16, v22
	v_lshlrev_b32_e32 v23, 16, v23
	v_lshlrev_b32_e32 v25, 16, v25
	v_mul_f32_e32 v21, v234, v21
	v_mul_f32_e32 v22, v235, v22
	v_mul_f32_e32 v23, v236, v23
	v_mul_f32_e32 v25, v237, v25
	ds_read_b128 v[234:237], v56 offset:52576
	s_waitcnt lgkmcnt(1)
	v_lshlrev_b32_e32 v26, 16, v26
	v_lshlrev_b32_e32 v28, 16, v28
	v_lshlrev_b32_e32 v29, 16, v29
	v_lshlrev_b32_e32 v31, 16, v31
	v_mul_f32_e32 v26, v238, v26
	v_mul_f32_e32 v28, v239, v28
	v_mul_f32_e32 v29, v240, v29
	v_mul_f32_e32 v31, v241, v31
	ds_read_b128 v[238:241], v56 offset:52592
	s_waitcnt lgkmcnt(1)
	v_lshlrev_b32_e32 v32, 16, v32
	v_lshlrev_b32_e32 v43, 16, v43
	v_lshlrev_b32_e32 v47, 16, v47
	v_lshlrev_b32_e32 v50, 16, v50
	v_mul_f32_e32 v32, v234, v32
	v_mul_f32_e32 v43, v235, v43
	v_mul_f32_e32 v47, v236, v47
	v_mul_f32_e32 v50, v237, v50
	ds_read_b128 v[234:237], v56 offset:52608
	s_waitcnt lgkmcnt(1)
	v_lshlrev_b32_e32 v52, 16, v52
	v_lshlrev_b32_e32 v107, 16, v107
	v_lshlrev_b32_e32 v106, 16, v106
	v_lshlrev_b32_e32 v84, 16, v84
	v_mul_f32_e32 v52, v238, v52
	v_mul_f32_e32 v107, v239, v107
	v_mul_f32_e32 v106, v240, v106
	v_mul_f32_e32 v84, v241, v84
	ds_read_b128 v[238:241], v56 offset:52624
	s_waitcnt vmcnt(0)
	s_waitcnt lgkmcnt(1)
	v_lshlrev_b32_e32 v86, 16, v86
	v_lshlrev_b32_e32 v88, 16, v88
	v_lshlrev_b32_e32 v90, 16, v90
	v_lshlrev_b32_e32 v92, 16, v92
	v_mul_f32_e32 v86, v234, v86
	v_mul_f32_e32 v88, v235, v88
	v_mul_f32_e32 v90, v236, v90
	v_mul_f32_e32 v92, v237, v92
	ds_read_b128 v[234:237], v56 offset:52640
	s_waitcnt lgkmcnt(1)
	v_lshlrev_b32_e32 v94, 16, v94
	v_lshlrev_b32_e32 v96, 16, v96
	v_lshlrev_b32_e32 v98, 16, v98
	v_lshlrev_b32_e32 v100, 16, v100
	v_mul_f32_e32 v94, v238, v94
	v_mul_f32_e32 v96, v239, v96
	v_mul_f32_e32 v98, v240, v98
	v_mul_f32_e32 v100, v241, v100
	ds_read_b128 v[238:241], v56 offset:52656
	s_waitcnt lgkmcnt(1)
	v_lshlrev_b32_e32 v103, 16, v103
	v_lshlrev_b32_e32 v105, 16, v105
	v_lshlrev_b32_e32 v104, 16, v104
	v_lshlrev_b32_e32 v102, 16, v102
	v_mul_f32_e32 v103, v234, v103
	v_mul_f32_e32 v105, v235, v105
	v_mul_f32_e32 v104, v236, v104
	v_mul_f32_e32 v102, v237, v102
	ds_read_b128 v[234:237], v56 offset:52672
	s_waitcnt lgkmcnt(1)
	v_lshlrev_b32_e32 v101, 16, v101
	v_lshlrev_b32_e32 v99, 16, v99
	v_lshlrev_b32_e32 v97, 16, v97
	v_lshlrev_b32_e32 v95, 16, v95
	v_mul_f32_e32 v101, v238, v101
	v_mul_f32_e32 v99, v239, v99
	v_mul_f32_e32 v97, v240, v97
	v_mul_f32_e32 v95, v241, v95
	ds_read_b128 v[238:241], v56 offset:52688
	s_waitcnt lgkmcnt(1)
	v_lshlrev_b32_e32 v93, 16, v93
	v_lshlrev_b32_e32 v91, 16, v91
	v_lshlrev_b32_e32 v89, 16, v89
	v_lshlrev_b32_e32 v87, 16, v87
	v_mul_f32_e32 v93, v234, v93
	v_mul_f32_e32 v91, v235, v91
	v_mul_f32_e32 v89, v236, v89
	v_mul_f32_e32 v87, v237, v87
	ds_read_b128 v[234:237], v56 offset:52704
	s_waitcnt lgkmcnt(1)
	v_lshlrev_b32_e32 v85, 16, v85
	v_lshlrev_b32_e32 v83, 16, v83
	v_lshlrev_b32_e32 v53, 16, v53
	v_lshlrev_b32_e32 v51, 16, v51
	v_mul_f32_e32 v85, v238, v85
	v_mul_f32_e32 v83, v239, v83
	v_mul_f32_e32 v53, v240, v53
	v_mul_f32_e32 v51, v241, v51
	ds_read_b128 v[238:241], v56 offset:52720
	s_waitcnt lgkmcnt(1)
	v_lshlrev_b32_e32 v45, 16, v45
	v_lshlrev_b32_e32 v33, 16, v33
	v_lshlrev_b32_e32 v30, 16, v30
	v_lshlrev_b32_e32 v27, 16, v27
	v_mul_f32_e32 v45, v234, v45
	v_mul_f32_e32 v33, v235, v33
	v_mul_f32_e32 v30, v236, v30
	v_mul_f32_e32 v27, v237, v27
	s_waitcnt lgkmcnt(0)
	v_lshlrev_b32_e32 v24, 16, v24
	v_lshlrev_b32_e32 v20, 16, v20
	v_lshlrev_b32_e32 v16, 16, v16
	v_lshlrev_b32_e32 v11, 16, v11
	v_mul_f32_e32 v24, v238, v24
	v_mul_f32_e32 v20, v239, v20
	v_mul_f32_e32 v16, v240, v16
	v_mul_f32_e32 v11, v241, v11
	s_and_saveexec_b64 s[38:39], s[36:37]
	s_cbranch_execz .Lc1_noexp
; DI void phase_gdn_c1(const Ctx& c) {
;     ...
;         if (ht >= 128) v *= __expf(gcs[i]);
;         sol[i] = v;
	ds_read_b128 v[242:245], v56 offset:52224
	ds_read_b128 v[246:249], v56 offset:52240
	s_waitcnt lgkmcnt(1)
	v_mul_f32_e32 v242, 0x3fb8aa3b, v242
	v_mul_f32_e32 v243, 0x3fb8aa3b, v243
	v_mul_f32_e32 v244, 0x3fb8aa3b, v244
	v_mul_f32_e32 v245, 0x3fb8aa3b, v245
	v_exp_f32_e32 v242, v242
	v_exp_f32_e32 v243, v243
	v_exp_f32_e32 v244, v244
	v_exp_f32_e32 v245, v245
	s_nop 0
	v_mul_f32_e32 v4, v4, v242
	v_mul_f32_e32 v5, v5, v243
	v_mul_f32_e32 v6, v6, v244
	v_mul_f32_e32 v7, v7, v245
	ds_read_b128 v[242:245], v56 offset:52256
	s_waitcnt lgkmcnt(1)
	v_mul_f32_e32 v246, 0x3fb8aa3b, v246
	v_mul_f32_e32 v247, 0x3fb8aa3b, v247
	v_mul_f32_e32 v248, 0x3fb8aa3b, v248
	v_mul_f32_e32 v249, 0x3fb8aa3b, v249
	v_exp_f32_e32 v246, v246
	v_exp_f32_e32 v247, v247
	v_exp_f32_e32 v248, v248
	v_exp_f32_e32 v249, v249
	s_nop 0
	v_mul_f32_e32 v8, v8, v246
	v_mul_f32_e32 v9, v9, v247
	v_mul_f32_e32 v10, v10, v248
	v_mul_f32_e32 v12, v12, v249
	ds_read_b128 v[246:249], v56 offset:52272
	s_waitcnt lgkmcnt(1)
	v_mul_f32_e32 v242, 0x3fb8aa3b, v242
	v_mul_f32_e32 v243, 0x3fb8aa3b, v243
	v_mul_f32_e32 v244, 0x3fb8aa3b, v244
	v_mul_f32_e32 v245, 0x3fb8aa3b, v245
	v_exp_f32_e32 v242, v242
	v_exp_f32_e32 v243, v243
	v_exp_f32_e32 v244, v244
	v_exp_f32_e32 v245, v245
	s_nop 0
	v_mul_f32_e32 v13, v13, v242
	v_mul_f32_e32 v15, v15, v243
	v_mul_f32_e32 v14, v14, v244
	v_mul_f32_e32 v109, v109, v245
	ds_read_b128 v[242:245], v56 offset:52288
	s_waitcnt lgkmcnt(1)
	v_mul_f32_e32 v246, 0x3fb8aa3b, v246
	v_mul_f32_e32 v247, 0x3fb8aa3b, v247
	v_mul_f32_e32 v248, 0x3fb8aa3b, v248
	v_mul_f32_e32 v249, 0x3fb8aa3b, v249
	v_exp_f32_e32 v246, v246
	v_exp_f32_e32 v247, v247
	v_exp_f32_e32 v248, v248
	v_exp_f32_e32 v249, v249
	s_nop 0
	v_mul_f32_e32 v17, v17, v246
	v_mul_f32_e32 v108, v108, v247
	v_mul_f32_e32 v18, v18, v248
	v_mul_f32_e32 v19, v19, v249
	ds_read_b128 v[246:249], v56 offset:52304
	s_waitcnt lgkmcnt(1)
	v_mul_f32_e32 v242, 0x3fb8aa3b, v242
	v_mul_f32_e32 v243, 0x3fb8aa3b, v243
	v_mul_f32_e32 v244, 0x3fb8aa3b, v244
	v_mul_f32_e32 v245, 0x3fb8aa3b, v245
	v_exp_f32_e32 v242, v242
	v_exp_f32_e32 v243, v243
	v_exp_f32_e32 v244, v244
	v_exp_f32_e32 v245, v245
	s_nop 0
	v_mul_f32_e32 v21, v21, v242
	v_mul_f32_e32 v22, v22, v243
	v_mul_f32_e32 v23, v23, v244
	v_mul_f32_e32 v25, v25, v245
	ds_read_b128 v[242:245], v56 offset:52320
	s_waitcnt lgkmcnt(1)
	v_mul_f32_e32 v246, 0x3fb8aa3b, v246
	v_mul_f32_e32 v247, 0x3fb8aa3b, v247
	v_mul_f32_e32 v248, 0x3fb8aa3b, v248
	v_mul_f32_e32 v249, 0x3fb8aa3b, v249
	v_exp_f32_e32 v246, v246
	v_exp_f32_e32 v247, v247
	v_exp_f32_e32 v248, v248
	v_exp_f32_e32 v249, v249
	s_nop 0
	v_mul_f32_e32 v26, v26, v246
	v_mul_f32_e32 v28, v28, v247
	v_mul_f32_e32 v29, v29, v248
	v_mul_f32_e32 v31, v31, v249
	ds_read_b128 v[246:249], v56 offset:52336
	s_waitcnt lgkmcnt(1)
	v_mul_f32_e32 v242, 0x3fb8aa3b, v242
	v_mul_f32_e32 v243, 0x3fb8aa3b, v243
	v_mul_f32_e32 v244, 0x3fb8aa3b, v244
	v_mul_f32_e32 v245, 0x3fb8aa3b, v245
	v_exp_f32_e32 v242, v242
	v_exp_f32_e32 v243, v243
	v_exp_f32_e32 v244, v244
	v_exp_f32_e32 v245, v245
	s_nop 0
	v_mul_f32_e32 v32, v32, v242
	v_mul_f32_e32 v43, v43, v243
	v_mul_f32_e32 v47, v47, v244
	v_mul_f32_e32 v50, v50, v245
	ds_read_b128 v[242:245], v56 offset:52352
	s_waitcnt lgkmcnt(1)
	v_mul_f32_e32 v246, 0x3fb8aa3b, v246
	v_mul_f32_e32 v247, 0x3fb8aa3b, v247
	v_mul_f32_e32 v248, 0x3fb8aa3b, v248
	v_mul_f32_e32 v249, 0x3fb8aa3b, v249
	v_exp_f32_e32 v246, v246
	v_exp_f32_e32 v247, v247
	v_exp_f32_e32 v248, v248
	v_exp_f32_e32 v249, v249
	s_nop 0
	v_mul_f32_e32 v52, v52, v246
	v_mul_f32_e32 v107, v107, v247
	v_mul_f32_e32 v106, v106, v248
	v_mul_f32_e32 v84, v84, v249
	ds_read_b128 v[246:249], v56 offset:52368
	s_waitcnt lgkmcnt(1)
; DI float bf2f(bf16 b) { return __uint_as_float(((unsigned)b) << 16); }
; DI void phase_gdn_c1(const Ctx& c) {
;     ...
;       for (int i = 0; i < 64; ++i) {
;         float v = bf2f(src[(size_t)(tokb + pos(i)) * 512 + h * 128 + cc]) * bs[i];
;         if (ht >= 128) v *= __expf(gcs[i]);
;         sol[i] = v;
;       }
	v_mul_f32_e32 v242, 0x3fb8aa3b, v242
	v_mul_f32_e32 v243, 0x3fb8aa3b, v243
	v_mul_f32_e32 v244, 0x3fb8aa3b, v244
	v_mul_f32_e32 v245, 0x3fb8aa3b, v245
	v_exp_f32_e32 v242, v242
	v_exp_f32_e32 v243, v243
	v_exp_f32_e32 v244, v244
	v_exp_f32_e32 v245, v245
	s_nop 0
	v_mul_f32_e32 v86, v86, v242
	v_mul_f32_e32 v88, v88, v243
	v_mul_f32_e32 v90, v90, v244
	v_mul_f32_e32 v92, v92, v245
	ds_read_b128 v[242:245], v56 offset:52384
	s_waitcnt lgkmcnt(1)
	v_mul_f32_e32 v246, 0x3fb8aa3b, v246
	v_mul_f32_e32 v247, 0x3fb8aa3b, v247
	v_mul_f32_e32 v248, 0x3fb8aa3b, v248
	v_mul_f32_e32 v249, 0x3fb8aa3b, v249
	v_exp_f32_e32 v246, v246
	v_exp_f32_e32 v247, v247
	v_exp_f32_e32 v248, v248
	v_exp_f32_e32 v249, v249
	s_nop 0
	v_mul_f32_e32 v94, v94, v246
	v_mul_f32_e32 v96, v96, v247
	v_mul_f32_e32 v98, v98, v248
	v_mul_f32_e32 v100, v100, v249
	ds_read_b128 v[246:249], v56 offset:52400
	s_waitcnt lgkmcnt(1)
	v_mul_f32_e32 v242, 0x3fb8aa3b, v242
	v_mul_f32_e32 v243, 0x3fb8aa3b, v243
	v_mul_f32_e32 v244, 0x3fb8aa3b, v244
	v_mul_f32_e32 v245, 0x3fb8aa3b, v245
	v_exp_f32_e32 v242, v242
	v_exp_f32_e32 v243, v243
	v_exp_f32_e32 v244, v244
	v_exp_f32_e32 v245, v245
	s_nop 0
	v_mul_f32_e32 v103, v103, v242
	v_mul_f32_e32 v105, v105, v243
	v_mul_f32_e32 v104, v104, v244
	v_mul_f32_e32 v102, v102, v245
	ds_read_b128 v[242:245], v56 offset:52416
	s_waitcnt lgkmcnt(1)
	v_mul_f32_e32 v246, 0x3fb8aa3b, v246
	v_mul_f32_e32 v247, 0x3fb8aa3b, v247
	v_mul_f32_e32 v248, 0x3fb8aa3b, v248
	v_mul_f32_e32 v249, 0x3fb8aa3b, v249
	v_exp_f32_e32 v246, v246
	v_exp_f32_e32 v247, v247
	v_exp_f32_e32 v248, v248
	v_exp_f32_e32 v249, v249
	s_nop 0
	v_mul_f32_e32 v101, v101, v246
	v_mul_f32_e32 v99, v99, v247
	v_mul_f32_e32 v97, v97, v248
	v_mul_f32_e32 v95, v95, v249
	ds_read_b128 v[246:249], v56 offset:52432
	s_waitcnt lgkmcnt(1)
	v_mul_f32_e32 v242, 0x3fb8aa3b, v242
	v_mul_f32_e32 v243, 0x3fb8aa3b, v243
	v_mul_f32_e32 v244, 0x3fb8aa3b, v244
	v_mul_f32_e32 v245, 0x3fb8aa3b, v245
	v_exp_f32_e32 v242, v242
	v_exp_f32_e32 v243, v243
	v_exp_f32_e32 v244, v244
	v_exp_f32_e32 v245, v245
	s_nop 0
	v_mul_f32_e32 v93, v93, v242
	v_mul_f32_e32 v91, v91, v243
	v_mul_f32_e32 v89, v89, v244
	v_mul_f32_e32 v87, v87, v245
	ds_read_b128 v[242:245], v56 offset:52448
	s_waitcnt lgkmcnt(1)
	v_mul_f32_e32 v246, 0x3fb8aa3b, v246
	v_mul_f32_e32 v247, 0x3fb8aa3b, v247
	v_mul_f32_e32 v248, 0x3fb8aa3b, v248
	v_mul_f32_e32 v249, 0x3fb8aa3b, v249
	v_exp_f32_e32 v246, v246
	v_exp_f32_e32 v247, v247
	v_exp_f32_e32 v248, v248
	v_exp_f32_e32 v249, v249
	s_nop 0
	v_mul_f32_e32 v85, v85, v246
	v_mul_f32_e32 v83, v83, v247
	v_mul_f32_e32 v53, v53, v248
	v_mul_f32_e32 v51, v51, v249
	ds_read_b128 v[246:249], v56 offset:52464
	s_waitcnt lgkmcnt(1)
	v_mul_f32_e32 v242, 0x3fb8aa3b, v242
	v_mul_f32_e32 v243, 0x3fb8aa3b, v243
	v_mul_f32_e32 v244, 0x3fb8aa3b, v244
	v_mul_f32_e32 v245, 0x3fb8aa3b, v245
	v_exp_f32_e32 v242, v242
	v_exp_f32_e32 v243, v243
	v_exp_f32_e32 v244, v244
	v_exp_f32_e32 v245, v245
	s_nop 0
	v_mul_f32_e32 v45, v45, v242
	v_mul_f32_e32 v33, v33, v243
	v_mul_f32_e32 v30, v30, v244
	v_mul_f32_e32 v27, v27, v245
	s_waitcnt lgkmcnt(0)
	v_mul_f32_e32 v246, 0x3fb8aa3b, v246
	v_mul_f32_e32 v247, 0x3fb8aa3b, v247
	v_mul_f32_e32 v248, 0x3fb8aa3b, v248
	v_mul_f32_e32 v249, 0x3fb8aa3b, v249
	v_exp_f32_e32 v246, v246
	v_exp_f32_e32 v247, v247
	v_exp_f32_e32 v248, v248
	v_exp_f32_e32 v249, v249
	s_nop 0
	v_mul_f32_e32 v24, v24, v246
	v_mul_f32_e32 v20, v20, v247
	v_mul_f32_e32 v16, v16, v248
	v_mul_f32_e32 v11, v11, v249

; DI float bf2f(bf16 b) { return __uint_as_float(((unsigned)b) << 16); }
; DI float cos2pi(float x) { return __builtin_amdgcn_cosf(x); }
; DI float sin2pi(float x) { return __builtin_amdgcn_sinf(x); }
; DI void hyena_item(const Ctx& c, int ch, float* red) {
;     ...
;       for (int p = 0; p < 2; ++p) {
; #pragma unroll 4
;         for (int n = gtid; n < L; n += NTG) {
;           const float a = bf2f(zin[r0 + n]), b = bf2f(zin[r1 + n]);
;           if (p == 0) bufg[n] = make_float2(a, b);
;           else {
;             const float fr = (float)n * i2L; const float cs = cos2pi(fr), sn = sin2pi(fr);
;             bufg[n] = make_float2(a * cs + b * sn, b * cs - a * sn);
;           }
;         }
;         __syncthreads();
.LBB0_666:
	s_xor_b64 s[42:43], s[0:1], -1
	s_lshl_b32 s82, s61, 1
	v_lshlrev_b32_e32 v252, 1, v38
	v_mov_b32_e32 v253, 0
	v_mov_b32_e32 v250, v38
	v_lshl_add_u32 v251, v38, 3, v40
	v_lshl_add_u64 v[246:247], v[12:13], 0, v[252:253]
	v_lshl_add_u64 v[248:249], v[16:17], 0, v[252:253]
	s_mov_b32 s100, 0
.Lhz_loop:
	global_load_ushort v230, v[246:247], off
	global_load_ushort v238, v[248:249], off
	v_lshl_add_u64 v[246:247], v[246:247], 0, s[82:83]
	v_lshl_add_u64 v[248:249], v[248:249], 0, s[82:83]
	global_load_ushort v231, v[246:247], off
	global_load_ushort v239, v[248:249], off
	v_lshl_add_u64 v[246:247], v[246:247], 0, s[82:83]
	v_lshl_add_u64 v[248:249], v[248:249], 0, s[82:83]
	global_load_ushort v232, v[246:247], off
	global_load_ushort v240, v[248:249], off
	v_lshl_add_u64 v[246:247], v[246:247], 0, s[82:83]
	v_lshl_add_u64 v[248:249], v[248:249], 0, s[82:83]
	global_load_ushort v233, v[246:247], off
	global_load_ushort v241, v[248:249], off
	v_lshl_add_u64 v[246:247], v[246:247], 0, s[82:83]
	v_lshl_add_u64 v[248:249], v[248:249], 0, s[82:83]
	global_load_ushort v234, v[246:247], off
	global_load_ushort v242, v[248:249], off
	v_lshl_add_u64 v[246:247], v[246:247], 0, s[82:83]
	v_lshl_add_u64 v[248:249], v[248:249], 0, s[82:83]
	global_load_ushort v235, v[246:247], off
	global_load_ushort v243, v[248:249], off
	v_lshl_add_u64 v[246:247], v[246:247], 0, s[82:83]
	v_lshl_add_u64 v[248:249], v[248:249], 0, s[82:83]
	global_load_ushort v236, v[246:247], off
	global_load_ushort v244, v[248:249], off
	v_lshl_add_u64 v[246:247], v[246:247], 0, s[82:83]
	v_lshl_add_u64 v[248:249], v[248:249], 0, s[82:83]
	global_load_ushort v237, v[246:247], off
	global_load_ushort v245, v[248:249], off
	v_lshl_add_u64 v[246:247], v[246:247], 0, s[82:83]
	v_lshl_add_u64 v[248:249], v[248:249], 0, s[82:83]
	s_waitcnt vmcnt(0)
	s_and_b64 vcc, exec, s[42:43]
	s_cbranch_vccz .Lhz_plain
	v_cvt_f32_i32_e32 v252, v250
	v_lshlrev_b32_e32 v230, 16, v230
	v_lshlrev_b32_e32 v238, 16, v238
	v_mul_f32_e32 v252, v199, v252
	v_add_u32_e32 v250, s61, v250
	v_sin_f32_e32 v253, v252
	v_cos_f32_e32 v254, v252
	s_nop 0
	v_mul_f32_e32 v255, v253, v238
	v_mul_f32_e32 v253, v253, v230
	v_fma_f32 v252, v254, v230, v255
	v_fma_f32 v253, v254, v238, -v253
	ds_write_b64 v251, v[252:253]
	v_add_u32_e32 v251, s92, v251
	v_cvt_f32_i32_e32 v252, v250
	v_lshlrev_b32_e32 v231, 16, v231
	v_lshlrev_b32_e32 v239, 16, v239
	v_mul_f32_e32 v252, v199, v252
	v_add_u32_e32 v250, s61, v250
	v_sin_f32_e32 v253, v252
	v_cos_f32_e32 v254, v252
	s_nop 0
	v_mul_f32_e32 v255, v253, v239
	v_mul_f32_e32 v253, v253, v231
	v_fma_f32 v252, v254, v231, v255
	v_fma_f32 v253, v254, v239, -v253
	ds_write_b64 v251, v[252:253]
	v_add_u32_e32 v251, s92, v251
	v_cvt_f32_i32_e32 v252, v250
	v_lshlrev_b32_e32 v232, 16, v232
	v_lshlrev_b32_e32 v240, 16, v240
	v_mul_f32_e32 v252, v199, v252
	v_add_u32_e32 v250, s61, v250
	v_sin_f32_e32 v253, v252
	v_cos_f32_e32 v254, v252
	s_nop 0
	v_mul_f32_e32 v255, v253, v240
	v_mul_f32_e32 v253, v253, v232
	v_fma_f32 v252, v254, v232, v255
	v_fma_f32 v253, v254, v240, -v253
	ds_write_b64 v251, v[252:253]
	v_add_u32_e32 v251, s92, v251
	v_cvt_f32_i32_e32 v252, v250
	v_lshlrev_b32_e32 v233, 16, v233
	v_lshlrev_b32_e32 v241, 16, v241
	v_mul_f32_e32 v252, v199, v252
	v_add_u32_e32 v250, s61, v250
	v_sin_f32_e32 v253, v252
	v_cos_f32_e32 v254, v252
	s_nop 0
	v_mul_f32_e32 v255, v253, v241
	v_mul_f32_e32 v253, v253, v233
	v_fma_f32 v252, v254, v233, v255
	v_fma_f32 v253, v254, v241, -v253
	ds_write_b64 v251, v[252:253]
	v_add_u32_e32 v251, s92, v251
	v_cvt_f32_i32_e32 v252, v250
	v_lshlrev_b32_e32 v234, 16, v234
	v_lshlrev_b32_e32 v242, 16, v242
	v_mul_f32_e32 v252, v199, v252
	v_add_u32_e32 v250, s61, v250
	v_sin_f32_e32 v253, v252
	v_cos_f32_e32 v254, v252
	s_nop 0
	v_mul_f32_e32 v255, v253, v242
	v_mul_f32_e32 v253, v253, v234
	v_fma_f32 v252, v254, v234, v255
	v_fma_f32 v253, v254, v242, -v253
	ds_write_b64 v251, v[252:253]
	v_add_u32_e32 v251, s92, v251
	v_cvt_f32_i32_e32 v252, v250
	v_lshlrev_b32_e32 v235, 16, v235
	v_lshlrev_b32_e32 v243, 16, v243
	v_mul_f32_e32 v252, v199, v252
	v_add_u32_e32 v250, s61, v250
	v_sin_f32_e32 v253, v252
	v_cos_f32_e32 v254, v252
	s_nop 0
	v_mul_f32_e32 v255, v253, v243
	v_mul_f32_e32 v253, v253, v235
	v_fma_f32 v252, v254, v235, v255
	v_fma_f32 v253, v254, v243, -v253
	ds_write_b64 v251, v[252:253]
	v_add_u32_e32 v251, s92, v251
	v_cvt_f32_i32_e32 v252, v250
	v_lshlrev_b32_e32 v236, 16, v236
	v_lshlrev_b32_e32 v244, 16, v244
	v_mul_f32_e32 v252, v199, v252
	v_add_u32_e32 v250, s61, v250
	v_sin_f32_e32 v253, v252
	v_cos_f32_e32 v254, v252
	s_nop 0
	v_mul_f32_e32 v255, v253, v244
	v_mul_f32_e32 v253, v253, v236
	v_fma_f32 v252, v254, v236, v255
	v_fma_f32 v253, v254, v244, -v253
	ds_write_b64 v251, v[252:253]
	v_add_u32_e32 v251, s92, v251
	v_cvt_f32_i32_e32 v252, v250
	v_lshlrev_b32_e32 v237, 16, v237
	v_lshlrev_b32_e32 v245, 16, v245
	v_mul_f32_e32 v252, v199, v252
	v_add_u32_e32 v250, s61, v250
	v_sin_f32_e32 v253, v252
	v_cos_f32_e32 v254, v252
	s_nop 0
	v_mul_f32_e32 v255, v253, v245
	v_mul_f32_e32 v253, v253, v237
	v_fma_f32 v252, v254, v237, v255
	v_fma_f32 v253, v254, v245, -v253
	ds_write_b64 v251, v[252:253]
	v_add_u32_e32 v251, s92, v251
	s_branch .Lhz_next
.Lhz_plain:
	v_lshlrev_b32_e32 v252, 16, v230
	v_lshlrev_b32_e32 v253, 16, v238
	ds_write_b64 v251, v[252:253]
	v_add_u32_e32 v251, s92, v251
	v_lshlrev_b32_e32 v252, 16, v231
	v_lshlrev_b32_e32 v253, 16, v239
	ds_write_b64 v251, v[252:253]
	v_add_u32_e32 v251, s92, v251
	v_lshlrev_b32_e32 v252, 16, v232
	v_lshlrev_b32_e32 v253, 16, v240
	ds_write_b64 v251, v[252:253]
	v_add_u32_e32 v251, s92, v251
	v_lshlrev_b32_e32 v252, 16, v233
	v_lshlrev_b32_e32 v253, 16, v241
	ds_write_b64 v251, v[252:253]
	v_add_u32_e32 v251, s92, v251
	v_lshlrev_b32_e32 v252, 16, v234
	v_lshlrev_b32_e32 v253, 16, v242
	ds_write_b64 v251, v[252:253]
	v_add_u32_e32 v251, s92, v251
	v_lshlrev_b32_e32 v252, 16, v235
	v_lshlrev_b32_e32 v253, 16, v243
	ds_write_b64 v251, v[252:253]
	v_add_u32_e32 v251, s92, v251
	v_lshlrev_b32_e32 v252, 16, v236
	v_lshlrev_b32_e32 v253, 16, v244
	ds_write_b64 v251, v[252:253]
	v_add_u32_e32 v251, s92, v251
	v_lshlrev_b32_e32 v252, 16, v237
	v_lshlrev_b32_e32 v253, 16, v245
	ds_write_b64 v251, v[252:253]
	v_add_u32_e32 v251, s92, v251
.Lhz_next:
	s_add_i32 s100, s100, 1
	s_cmp_lg_u32 s100, 4
	s_cbranch_scc1 .Lhz_loop
	s_mov_b64 s[0:1], exec

; DI float bf2f(bf16 b) { return __uint_as_float(((unsigned)b) << 16); }
; DI float cos2pi(float x) { return __builtin_amdgcn_cosf(x); }
; DI float sin2pi(float x) { return __builtin_amdgcn_sinf(x); }
; DI void hyena_item(const Ctx& c, int ch, float* red) {
;     ...
;   #pragma unroll 4
;         for (int n = gtid; n < L; n += NTG) {
;             const float2 y = bufg[n], pt = PART[n];
;             const float fr = (float)n * i2L; const float cs = cos2pi(fr), sn = sin2pi(fr);
;             const float cx = (pt.x + (y.x * cs - y.y * sn)) * scale;
;             const float cy = (pt.y + (y.x * sn + y.y * cs)) * scale;
;             const float z0 = bf2f(zin[r0 + n]), z1 = bf2f(zin[r1 + n]);
;             const float g0 = bf2f(gate[r0 + n]), g1 = bf2f(gate[r1 + n]);
;             zo[r0 + n] = f2bf(g0 * (cx + skip * z0));
;             zo[r1 + n] = f2bf(g1 * (cy + skip * z1));
;           }
.LBB0_743:
	s_lshl_b32 s82, s61, 1
	v_lshlrev_b32_e32 v30, 1, v38
	v_mov_b32_e32 v31, 0
	v_lshlrev_b32_e32 v32, 3, v38
	v_mov_b32_e32 v33, 0
	v_mov_b32_e32 v254, v38
	v_lshl_add_u32 v255, v38, 3, v40
	v_lshl_add_u64 v[248:249], v[12:13], 0, v[30:31]
	v_lshl_add_u64 v[250:251], v[16:17], 0, v[30:31]
	v_lshl_add_u64 v[246:247], v[42:43], 0, v[32:33]
	v_add_lshl_u32 v252, v6, v38, 1
	v_add_lshl_u32 v253, v8, v38, 1
	s_mov_b32 s100, 0
.Lhf_loop:
	global_load_dwordx2 v[230:231], v[246:247], off
	global_load_ushort v102, v[248:249], off
	global_load_ushort v106, v[250:251], off
	v_mov_b32_e32 v64, v252
	v_mov_b32_e32 v68, v253
	ds_read_b64 v[238:239], v255
	global_load_ushort v110, v64, s[28:29]
	global_load_ushort v114, v68, s[28:29]
	v_lshl_add_u64 v[246:247], v[246:247], 0, s[92:93]
	v_lshl_add_u64 v[248:249], v[248:249], 0, s[82:83]
	v_lshl_add_u64 v[250:251], v[250:251], 0, s[82:83]
	v_add_u32_e32 v252, s82, v252
	v_add_u32_e32 v253, s82, v253
	v_add_u32_e32 v255, s92, v255
	global_load_dwordx2 v[232:233], v[246:247], off
	global_load_ushort v103, v[248:249], off
	global_load_ushort v107, v[250:251], off
	v_mov_b32_e32 v65, v252
	v_mov_b32_e32 v69, v253
	ds_read_b64 v[240:241], v255
	global_load_ushort v111, v65, s[28:29]
	global_load_ushort v115, v69, s[28:29]
	v_lshl_add_u64 v[246:247], v[246:247], 0, s[92:93]
	v_lshl_add_u64 v[248:249], v[248:249], 0, s[82:83]
	v_lshl_add_u64 v[250:251], v[250:251], 0, s[82:83]
	v_add_u32_e32 v252, s82, v252
	v_add_u32_e32 v253, s82, v253
	v_add_u32_e32 v255, s92, v255
	global_load_dwordx2 v[234:235], v[246:247], off
	global_load_ushort v104, v[248:249], off
	global_load_ushort v108, v[250:251], off
	v_mov_b32_e32 v66, v252
	v_mov_b32_e32 v70, v253
	ds_read_b64 v[242:243], v255
	global_load_ushort v112, v66, s[28:29]
	global_load_ushort v116, v70, s[28:29]
	v_lshl_add_u64 v[246:247], v[246:247], 0, s[92:93]
	v_lshl_add_u64 v[248:249], v[248:249], 0, s[82:83]
	v_lshl_add_u64 v[250:251], v[250:251], 0, s[82:83]
	v_add_u32_e32 v252, s82, v252
	v_add_u32_e32 v253, s82, v253
	v_add_u32_e32 v255, s92, v255
	global_load_dwordx2 v[236:237], v[246:247], off
	global_load_ushort v105, v[248:249], off
	global_load_ushort v109, v[250:251], off
	v_mov_b32_e32 v67, v252
	v_mov_b32_e32 v71, v253
	ds_read_b64 v[244:245], v255
	global_load_ushort v113, v67, s[28:29]
	global_load_ushort v117, v71, s[28:29]
	v_lshl_add_u64 v[246:247], v[246:247], 0, s[92:93]
	v_lshl_add_u64 v[248:249], v[248:249], 0, s[82:83]
	v_lshl_add_u64 v[250:251], v[250:251], 0, s[82:83]
	v_add_u32_e32 v252, s82, v252
	v_add_u32_e32 v253, s82, v253
	v_add_u32_e32 v255, s92, v255
	s_waitcnt vmcnt(0) lgkmcnt(0)
	v_cvt_f32_i32_e32 v30, v254
	v_add_u32_e32 v254, s61, v254
	v_mul_f32_e32 v30, v199, v30
	v_lshlrev_b32_e32 v102, 16, v102
	v_sin_f32_e32 v31, v30
	v_cos_f32_e32 v32, v30
	v_lshlrev_b32_e32 v106, 16, v106
	v_mul_f32_e32 v102, v0, v102
	v_mul_f32_e32 v33, v239, v31
	v_mul_f32_e32 v47, v239, v32
	v_fma_f32 v33, v238, v32, -v33
	v_fmac_f32_e32 v47, v238, v31
	v_mul_f32_e32 v106, v0, v106
	v_add_f32_e32 v33, v230, v33
	v_add_f32_e32 v47, v231, v47
	v_lshlrev_b32_e32 v110, 16, v110
	v_lshlrev_b32_e32 v114, 16, v114
	v_fmac_f32_e32 v102, v199, v33
	v_fmac_f32_e32 v106, v199, v47
	v_mul_f32_e32 v102, v102, v110
	v_mul_f32_e32 v106, v106, v114
	v_cvt_pk_bf16_f32 v102, v102, v102
	v_cvt_pk_bf16_f32 v106, v106, v106
	global_store_short v64, v102, s[36:37]
	global_store_short v68, v106, s[36:37]
	v_cvt_f32_i32_e32 v30, v254
	v_add_u32_e32 v254, s61, v254
	v_mul_f32_e32 v30, v199, v30
	v_lshlrev_b32_e32 v103, 16, v103
	v_sin_f32_e32 v31, v30
	v_cos_f32_e32 v32, v30
	v_lshlrev_b32_e32 v107, 16, v107
	v_mul_f32_e32 v103, v0, v103
	v_mul_f32_e32 v33, v241, v31
	v_mul_f32_e32 v47, v241, v32
	v_fma_f32 v33, v240, v32, -v33
	v_fmac_f32_e32 v47, v240, v31
	v_mul_f32_e32 v107, v0, v107
	v_add_f32_e32 v33, v232, v33
	v_add_f32_e32 v47, v233, v47
	v_lshlrev_b32_e32 v111, 16, v111
	v_lshlrev_b32_e32 v115, 16, v115
	v_fmac_f32_e32 v103, v199, v33
	v_fmac_f32_e32 v107, v199, v47
	v_mul_f32_e32 v103, v103, v111
	v_mul_f32_e32 v107, v107, v115
	v_cvt_pk_bf16_f32 v103, v103, v103
	v_cvt_pk_bf16_f32 v107, v107, v107
	global_store_short v65, v103, s[36:37]
	global_store_short v69, v107, s[36:37]
	v_cvt_f32_i32_e32 v30, v254
	v_add_u32_e32 v254, s61, v254
	v_mul_f32_e32 v30, v199, v30
	v_lshlrev_b32_e32 v104, 16, v104
	v_sin_f32_e32 v31, v30
	v_cos_f32_e32 v32, v30
	v_lshlrev_b32_e32 v108, 16, v108
	v_mul_f32_e32 v104, v0, v104
	v_mul_f32_e32 v33, v243, v31
	v_mul_f32_e32 v47, v243, v32
	v_fma_f32 v33, v242, v32, -v33
	v_fmac_f32_e32 v47, v242, v31
	v_mul_f32_e32 v108, v0, v108
	v_add_f32_e32 v33, v234, v33
	v_add_f32_e32 v47, v235, v47
	v_lshlrev_b32_e32 v112, 16, v112
	v_lshlrev_b32_e32 v116, 16, v116
	v_fmac_f32_e32 v104, v199, v33
	v_fmac_f32_e32 v108, v199, v47
	v_mul_f32_e32 v104, v104, v112
	v_mul_f32_e32 v108, v108, v116
	v_cvt_pk_bf16_f32 v104, v104, v104
	v_cvt_pk_bf16_f32 v108, v108, v108
	global_store_short v66, v104, s[36:37]
	global_store_short v70, v108, s[36:37]
	v_cvt_f32_i32_e32 v30, v254
	v_add_u32_e32 v254, s61, v254
	v_mul_f32_e32 v30, v199, v30
	v_lshlrev_b32_e32 v105, 16, v105
	v_sin_f32_e32 v31, v30
	v_cos_f32_e32 v32, v30
	v_lshlrev_b32_e32 v109, 16, v109
	v_mul_f32_e32 v105, v0, v105
	v_mul_f32_e32 v33, v245, v31
	v_mul_f32_e32 v47, v245, v32
	v_fma_f32 v33, v244, v32, -v33
	v_fmac_f32_e32 v47, v244, v31
	v_mul_f32_e32 v109, v0, v109
	v_add_f32_e32 v33, v236, v33
	v_add_f32_e32 v47, v237, v47
	v_lshlrev_b32_e32 v113, 16, v113
	v_lshlrev_b32_e32 v117, 16, v117
	v_fmac_f32_e32 v105, v199, v33
	v_fmac_f32_e32 v109, v199, v47
	v_mul_f32_e32 v105, v105, v113
	v_mul_f32_e32 v109, v109, v117
	v_cvt_pk_bf16_f32 v105, v105, v105
	v_cvt_pk_bf16_f32 v109, v109, v109
	global_store_short v67, v105, s[36:37]
	global_store_short v71, v109, s[36:37]
	s_add_i32 s100, s100, 1
	s_cmp_lg_u32 s100, 8
	s_cbranch_scc1 .Lhf_loop
	s_mov_b64 s[0:1], exec

; DI void gdn_scan_item(const Ctx& c, int item) {
;     ...
;   auto prefetch = [&](int n) {
;     const size_t ci = (size_t)(citem0 + n);
;     const bf16* pw = CW + ci * 8192 + srow * 128 + sseg;
;     rw0 = *(const uint4*)pw; rw1 = *(const uint4*)(pw + 8);
;     const bf16* pq = GQ + (size_t)(tokb + pos(n, srow)) * 512 + h * 128 + sseg;
;     rq0 = *(const uint4*)pq; rq1 = *(const uint4*)(pq + 8);
;     const bf16* pk = GK + (size_t)(tokb + pos(n, krow)) * 512 + h * 128 + kseg;
;     rk0 = *(const uint4*)pk; rk1 = *(const uint4*)(pk + 8);
;     ra = *(const uint4*)(CAQK + ci * 4096 + arow * 64 + aseg);
;     if (tid < 64) rgc = GC[ci * 64 + tid];
; #pragma unroll
;     for (int r = 0; r < 4; ++r) ru[r] = CU[ci * 8192 + (mi * 16 + q4 + r) * 128 + dvs * 32 + nj * 16 + fr];
;   };
.LBB0_777:
	s_or_b64 exec, exec, s[12:13]
	v_lshl_add_u64 v[78:79], s[8:9], 1, v[42:43]
	global_load_ushort v230, v[78:79], off
	global_load_ushort v231, v[78:79], off offset:512
	global_load_ushort v232, v[78:79], off offset:768
	s_nop 0
	global_load_ushort v233, v[78:79], off offset:256
	s_branch .LBB0_779

; DI void gdn_scan_item(const Ctx& c, int item) {
;     ...
;       f32x4 a1 = f32x4{0.f, 0.f, 0.f, 0.f};
; #pragma unroll
;       for (int k0 = 0; k0 < 128; k0 += 32) {
;         const bf16x8 a = *(const bf16x8*)(Wl + (mi * 16 + fr) * 136 + k0 + fq);
;         const bf16x8 b = *(const bf16x8*)(St + (nj * 16 + fr) * 136 + k0 + fq);
;         a1 = MFMA16(a, b, a1);
;       }
;       float vn[4], vs[4];
; #pragma unroll
;       for (int r = 0; r < 4; ++r) { vn[r] = ucur[r] - a1[r]; vs[r] = vn[r] * __expf(gl - gcs[mi * 16 + q4 + r]); }
;       uint2 p; p.x = pack2(vn[0], vn[1]); p.y = pack2(vn[2], vn[3]);
;       *(uint2*)(VNt + (nj * 16 + fr) * 72 + mi * 16 + q4) = p;
;       p.x = pack2(vs[0], vs[1]); p.y = pack2(vs[2], vs[3]);
;       *(uint2*)(VNs + (nj * 16 + fr) * 72 + mi * 16 + q4) = p;
;     }
;     __syncthreads();
;     {
;       f32x4 a1 = f32x4{0.f, 0.f, 0.f, 0.f}, a2 = f32x4{0.f, 0.f, 0.f, 0.f};
; #pragma unroll
;       for (int k0 = 0; k0 < 128; k0 += 32) {
;         const bf16x8 a = *(const bf16x8*)(Ql + (mi * 16 + fr) * 136 + k0 + fq);
;         const bf16x8 b = *(const bf16x8*)(St + (nj * 16 + fr) * 136 + k0 + fq);
;         a1 = MFMA16(a, b, a1);
;       }
; #pragma unroll
;       for (int k0 = 0; k0 < 64; k0 += 32) {
;         const bf16x8 a = *(const bf16x8*)(AQl + (mi * 16 + fr) * 72 + k0 + fq);
;         const bf16x8 b = *(const bf16x8*)(VNt + (nj * 16 + fr) * 72 + k0 + fq);
;         a2 = MFMA16(a, b, a2);
;       }
; #pragma unroll
;       for (int r = 0; r < 4; ++r) {
;         const int i = mi * 16 + q4 + r;
;         const float o = __expf(gcs[i]) * a1[r] + a2[r];
;         O[(size_t)(tokb + pos(n, i)) * 512 + h * 128 + dvs * 32 + nj * 16 + fr] = f2bf(o);
;       }
;     }
;     {
;       const float dec = __expf(gl);
; #pragma unroll
;       for (int jj = 0; jj < 2; ++jj) {
;         f32x4 a3 = f32x4{0.f, 0.f, 0.f, 0.f};
; #pragma unroll
;         for (int k0 = 0; k0 < 64; k0 += 32) {
;           const bf16x8 a = *(const bf16x8*)(Ktl + (w * 16 + fr) * 72 + k0 + fq);
;           const bf16x8 b = *(const bf16x8*)(VNs + (jj * 16 + fr) * 72 + k0 + fq);
;           a3 = MFMA16(a, b, a3);
;         }
; #pragma unroll
;         for (int r = 0; r < 4; ++r) S[jj][r] = dec * S[jj][r] + a3[r];
;       }
;     }
;     __syncthreads();
; #pragma unroll
;     for (int jj = 0; jj < 2; ++jj) {
.LBB0_779:
	ds_read_b128 v[78:81], v57
	ds_read_b128 v[82:85], v58 offset:62464
	ds_read_b128 v[86:89], v57 offset:64
	v_and_b32_e32 v107, 0xffff0000, v76
	v_lshlrev_b32_e32 v106, 16, v76
	v_mov_b32_e32 v108, s19
	ds_read_b128 v[90:93], v58 offset:62528
	ds_read_b128 v[94:97], v57 offset:128
	ds_read_b128 v[98:101], v58 offset:62592
	s_andn2_b64 vcc, exec, s[6:7]
	s_waitcnt lgkmcnt(4)
	v_mfma_f32_16x16x32_bf16 v[76:79], v[78:81], v[82:85], 0
	ds_read_b128 v[80:83], v57 offset:192
	ds_read_b128 v[102:105], v64
	ds_read_b32 v108, v108
	s_waitcnt lgkmcnt(5)
	v_mfma_f32_16x16x32_bf16 v[76:79], v[86:89], v[90:93], v[76:79]
	v_and_b32_e32 v89, 0xffff0000, v75
	v_lshlrev_b32_e32 v88, 16, v75
	s_waitcnt lgkmcnt(0)
	v_sub_f32_e32 v75, v108, v102
	ds_read_b128 v[84:87], v58 offset:62656
	v_mul_f32_e32 v75, 0x3fb8aa3b, v75
	v_mfma_f32_16x16x32_bf16 v[76:79], v[94:97], v[98:101], v[76:79]
	v_exp_f32_e32 v90, v75
	v_sub_f32_e32 v75, v108, v103
	v_mul_f32_e32 v75, 0x3fb8aa3b, v75
	v_exp_f32_e32 v91, v75
	v_sub_f32_e32 v75, v108, v104
	v_mul_f32_e32 v75, 0x3fb8aa3b, v75
	s_waitcnt lgkmcnt(0)
	v_mfma_f32_16x16x32_bf16 v[76:79], v[80:83], v[84:87], v[76:79]
	v_exp_f32_e32 v80, v75
	v_sub_f32_e32 v75, v108, v105
	v_mul_f32_e32 v75, 0x3fb8aa3b, v75
	v_exp_f32_e32 v81, v75
	s_nop 3
	v_pk_add_f32 v[76:77], v[106:107], v[76:77] neg_lo:[0,1] neg_hi:[0,1]
	v_pk_add_f32 v[78:79], v[88:89], v[78:79] neg_lo:[0,1] neg_hi:[0,1]
	v_pk_mul_f32 v[82:83], v[76:77], v[90:91]
	v_pk_mul_f32 v[80:81], v[78:79], v[80:81]
	v_cvt_pk_bf16_f32 v82, v82, v83
	v_cvt_pk_bf16_f32 v79, v78, v79
	v_cvt_pk_bf16_f32 v78, v76, v77
	v_cvt_pk_bf16_f32 v83, v80, v81
	ds_write_b64 v59, v[78:79]
	ds_write_b64 v60, v[82:83]
	s_waitcnt lgkmcnt(0)
	s_barrier
	ds_read_b128 v[76:79], v61 offset:53248
	ds_read_b128 v[80:83], v62
	ds_read_b128 v[84:87], v61 offset:53312
	ds_read_b128 v[88:91], v62 offset:64
	s_waitcnt lgkmcnt(2)
	v_mfma_f32_16x16x32_bf16 v[76:79], v[76:79], v[80:83], 0
	ds_read_b128 v[80:83], v57 offset:17408
	ds_read_b128 v[92:95], v58 offset:62464
	s_waitcnt lgkmcnt(2)
	v_mfma_f32_16x16x32_bf16 v[76:79], v[84:87], v[88:91], v[76:79]
	ds_read_b128 v[84:87], v57 offset:17472
	ds_read_b128 v[88:91], v58 offset:62528
	s_waitcnt lgkmcnt(2)
	v_mfma_f32_16x16x32_bf16 v[80:83], v[80:83], v[92:95], 0
	ds_read_b128 v[92:95], v57 offset:17536
	ds_read_b128 v[96:99], v58 offset:62592
	ds_read_b128 v[100:103], v57 offset:17600
	s_waitcnt lgkmcnt(3)
	v_mfma_f32_16x16x32_bf16 v[80:83], v[84:87], v[88:91], v[80:83]
	ds_read_b128 v[84:87], v64
	ds_read_b128 v[88:91], v58 offset:62656
	s_waitcnt lgkmcnt(1)
	v_mul_f32_e32 v75, 0x3fb8aa3b, v84
	v_mfma_f32_16x16x32_bf16 v[80:83], v[92:95], v[96:99], v[80:83]
	v_exp_f32_e32 v75, v75
	ds_read_b128 v[92:95], v70
	s_waitcnt lgkmcnt(1)
	v_mfma_f32_16x16x32_bf16 v[80:83], v[100:103], v[88:91], v[80:83]
	v_add_u32_e32 v91, s17, v65
	v_add_u32_e32 v90, s15, v53
	s_nop 5
	v_fma_f32 v75, v80, v75, v76
	v_add_u32_e32 v76, -1, v91
	v_cndmask_b32_e64 v76, v76, v90, s[0:1]
	v_add_u32_e32 v88, s14, v76
	v_mul_f32_e32 v76, 0x3fb8aa3b, v85
	v_exp_f32_e32 v76, v76
	v_ashrrev_i32_e32 v89, 31, v88
	v_lshlrev_b64 v[84:85], 10, v[88:89]
	v_cvt_pk_bf16_f32 v75, v75, s0
	v_lshl_add_u64 v[84:85], v[40:41], 0, v[84:85]
	global_store_short v[84:85], v75, off
	v_fma_f32 v75, v81, v76, v77
	v_add_u32_e32 v76, 1, v90
	v_add_u32_e32 v77, -2, v91
	v_cndmask_b32_e64 v76, v77, v76, s[0:1]
	v_mul_f32_e32 v80, 0x3fb8aa3b, v86
	v_add_u32_e32 v76, s14, v76
	v_exp_f32_e32 v80, v80
	v_ashrrev_i32_e32 v77, 31, v76
	v_lshlrev_b64 v[76:77], 10, v[76:77]
	v_cvt_pk_bf16_f32 v75, v75, s0
	v_lshl_add_u64 v[76:77], v[40:41], 0, v[76:77]
	global_store_short v[76:77], v75, off
	v_fma_f32 v75, v82, v80, v78
	v_mul_f32_e32 v78, 0x3fb8aa3b, v87
	v_exp_f32_e32 v78, v78
	v_add_u32_e32 v76, 2, v90
	v_add_u32_e32 v77, -3, v91
	v_cndmask_b32_e64 v76, v77, v76, s[0:1]
	v_add_u32_e32 v76, s14, v76
	v_fmac_f32_e32 v79, v83, v78
	ds_read_b128 v[80:83], v0 offset:34816
	v_ashrrev_i32_e32 v77, 31, v76
	v_lshlrev_b64 v[76:77], 10, v[76:77]
	v_cvt_pk_bf16_f32 v75, v75, s0
	v_lshl_add_u64 v[76:77], v[40:41], 0, v[76:77]
	global_store_short v[76:77], v75, off
	v_cvt_pk_bf16_f32 v75, v79, s0
	ds_read_b128 v[76:79], v0 offset:34880
	v_add_u32_e32 v84, 3, v90
	v_add_u32_e32 v85, -4, v91
	v_cndmask_b32_e64 v84, v85, v84, s[0:1]
	v_add_u32_e32 v96, s14, v84
	v_ashrrev_i32_e32 v97, 31, v96
	ds_read_b128 v[84:87], v70 offset:64
	s_waitcnt lgkmcnt(2)
	v_mfma_f32_16x16x32_bf16 v[88:91], v[80:83], v[92:95], 0
	v_lshlrev_b64 v[92:93], 10, v[96:97]
	v_lshl_add_u64 v[96:97], v[40:41], 0, v[92:93]
	ds_read_b128 v[92:95], v70 offset:2304
	s_waitcnt lgkmcnt(1)
	v_mfma_f32_16x16x32_bf16 v[84:87], v[76:79], v[84:87], v[88:91]
	global_store_short v[96:97], v75, off
	s_nop 1
	v_mul_f32_e32 v88, 0x3fb8aa3b, v108
	v_exp_f32_e32 v98, v88
	ds_read_b128 v[88:91], v70 offset:2368
	s_waitcnt lgkmcnt(1)
	v_mfma_f32_16x16x32_bf16 v[80:83], v[80:83], v[92:95], 0
	s_waitcnt lgkmcnt(0)
	v_pk_fma_f32 v[44:45], v[44:45], v[98:99], v[84:85] op_sel_hi:[1,0,1]
	v_pk_fma_f32 v[46:47], v[46:47], v[98:99], v[86:87] op_sel_hi:[1,0,1]
	v_mfma_f32_16x16x32_bf16 v[76:79], v[76:79], v[88:91], v[80:83]
	s_barrier
	s_nop 6
	v_pk_fma_f32 v[48:49], v[48:49], v[98:99], v[76:77] op_sel_hi:[1,0,1]
	v_pk_fma_f32 v[50:51], v[50:51], v[98:99], v[78:79] op_sel_hi:[1,0,1]
	v_cvt_pk_bf16_f32 v77, v46, v47
	v_cvt_pk_bf16_f32 v76, v44, v45
	ds_write_b64 v71, v[76:77] offset:62464
	v_cvt_pk_bf16_f32 v77, v50, v51
	v_cvt_pk_bf16_f32 v76, v48, v49
	ds_write_b64 v72, v[76:77] offset:62464
	s_cbranch_vccnz .LBB0_773
	s_waitcnt vmcnt(0)
	s_mov_b32 s8, 0x5040100
	v_perm_b32 v74, v232, v231, s8
	v_perm_b32 v73, v233, v230, s8
	ds_write_b128 v54, v[6:9]
	ds_write_b128 v54, v[2:5] offset:16
	ds_write_b128 v54, v[14:17] offset:17408
	ds_write_b128 v54, v[10:13] offset:17424
	ds_write_b16 v55, v22 offset:34816
	ds_write_b16_d16_hi v55, v22 offset:34960
	ds_write_b16 v55, v23 offset:35104
	ds_write_b16_d16_hi v55, v23 offset:35248
	ds_write_b16 v55, v24 offset:35392
	ds_write_b16_d16_hi v55, v24 offset:35536
	ds_write_b16 v55, v25 offset:35680
	ds_write_b16_d16_hi v55, v25 offset:35824
	ds_write_b16 v55, v18 offset:35968
	ds_write_b16_d16_hi v55, v18 offset:36112
	ds_write_b16 v55, v19 offset:36256
	ds_write_b16_d16_hi v55, v19 offset:36400
	ds_write_b16 v55, v20 offset:36544
	ds_write_b16_d16_hi v55, v20 offset:36688
	ds_write_b16 v55, v21 offset:36832
	ds_write_b16_d16_hi v55, v21 offset:36976
	ds_write_b128 v56, v[26:29] offset:53248
	s_and_saveexec_b64 s[6:7], s[4:5]
	s_cbranch_execz .LBB0_772
	ds_write_b32 v63, v52
	s_branch .LBB0_772

; extern "C" __global__ void __launch_bounds__(NTHR) mega(Params p) {
;   extern __shared__ __attribute__((aligned(16))) char smem[];
;   __shared__ int s_item;
	.amdhsa_kernel mega
		.amdhsa_group_segment_fixed_size 80
		.amdhsa_private_segment_fixed_size 0
		.amdhsa_kernarg_size 504
		.amdhsa_user_sgpr_count 2
		.amdhsa_user_sgpr_dispatch_ptr 0
		.amdhsa_user_sgpr_queue_ptr 0
		.amdhsa_user_sgpr_kernarg_segment_ptr 1
		.amdhsa_user_sgpr_dispatch_id 0
		.amdhsa_user_sgpr_kernarg_preload_length 0
		.amdhsa_user_sgpr_kernarg_preload_offset 0
		.amdhsa_user_sgpr_private_segment_size 0
		.amdhsa_uses_dynamic_stack 0
		.amdhsa_enable_private_segment 0
		.amdhsa_system_sgpr_workgroup_id_x 1
		.amdhsa_system_sgpr_workgroup_id_y 0
		.amdhsa_system_sgpr_workgroup_id_z 0
		.amdhsa_system_sgpr_workgroup_info 0
		.amdhsa_system_vgpr_workitem_id 2
		.amdhsa_next_free_vgpr 256
		.amdhsa_next_free_sgpr 102
		.amdhsa_accum_offset 256
		.amdhsa_reserve_vcc 1
		.amdhsa_float_round_mode_32 0
		.amdhsa_float_round_mode_16_64 0
		.amdhsa_float_denorm_mode_32 3
		.amdhsa_float_denorm_mode_16_64 3
		.amdhsa_dx10_clamp 1
		.amdhsa_ieee_mode 1
		.amdhsa_fp16_overflow 0
		.amdhsa_tg_split 0
		.amdhsa_exception_fp_ieee_invalid_op 0
		.amdhsa_exception_fp_denorm_src 0
		.amdhsa_exception_fp_ieee_div_zero 0
		.amdhsa_exception_fp_ieee_overflow 0
		.amdhsa_exception_fp_ieee_underflow 0
		.amdhsa_exception_fp_ieee_inexact 0
		.amdhsa_exception_int_div_zero 0
	.end_amdhsa_kernel

; extern "C" __global__ void __launch_bounds__(NTHR) mega(Params p) {
;   extern __shared__ __attribute__((aligned(16))) char smem[];
;   __shared__ int s_item;
amdhsa.kernels:
  - .agpr_count:     0
    .args:
      - .offset:         0
        .size:           248
        .value_kind:     by_value
      - .offset:         248
        .size:           4
        .value_kind:     hidden_block_count_x
      - .offset:         252
        .size:           4
        .value_kind:     hidden_block_count_y
      - .offset:         256
        .size:           4
        .value_kind:     hidden_block_count_z
      - .offset:         260
        .size:           2
        .value_kind:     hidden_group_size_x
      - .offset:         262
        .size:           2
        .value_kind:     hidden_group_size_y
      - .offset:         264
        .size:           2
        .value_kind:     hidden_group_size_z
      - .offset:         266
        .size:           2
        .value_kind:     hidden_remainder_x
      - .offset:         268
        .size:           2
        .value_kind:     hidden_remainder_y
      - .offset:         270
        .size:           2
        .value_kind:     hidden_remainder_z
      - .offset:         288
        .size:           8
        .value_kind:     hidden_global_offset_x
      - .offset:         296
        .size:           8
        .value_kind:     hidden_global_offset_y
      - .offset:         304
        .size:           8
        .value_kind:     hidden_global_offset_z
      - .offset:         312
        .size:           2
        .value_kind:     hidden_grid_dims
      - .offset:         336
        .size:           8
        .value_kind:     hidden_multigrid_sync_arg
      - .offset:         368
        .size:           4
        .value_kind:     hidden_dynamic_lds_size
    .group_segment_fixed_size: 80
    .kernarg_segment_align: 8
    .kernarg_segment_size: 504
    .language:       OpenCL C
    .language_version:
      - 2
      - 0
    .max_flat_workgroup_size: 512
    .name:           mega
    .private_segment_fixed_size: 0
    .sgpr_count:     108
    .sgpr_spill_count: 312
    .symbol:         mega.kd
    .uniform_work_group_size: 1
    .uses_dynamic_stack: false
    .vgpr_count:     256
    .vgpr_spill_count: 0
    .wavefront_size: 64
